# v33 + attention row-max exchange via permlane32 swap (3 sites)
# baseline (speedup 1.0000x reference)
; #define LAS __attribute__((address_space(3)))
; __device__ __forceinline__ int tpos(int t) { return (t & ~2047) | ((t & 15) << 7) | ((t & 2047) >> 4); }
; __device__ __forceinline__ void attn_load(const bf16_t* proj, const AttnItem& t, u32x4 (&kv)[6], u32x4 (&vv)[6], int tid) {
;     const int nb0 = t.nb & ~1;
;     const bf16_t* kb = proj + (size_t)NB * NH * SEQ * HD + (size_t)(t.b * NH + t.h) * SEQ * 2 * HD;
; #pragma unroll
;     for (int c = 0; c < 6; ++c) { const int idx = tid + 512 * c, j = idx >> 3, ch = idx & 7; const int sidx = (nb0 - 1) * 128 + j;
;         const int sj = sidx >= 0 ? sidx : sidx + 128;
;         const bf16_t* p = kb + (size_t)tpos(sj * t.dil + t.r) * 2 * HD + ch * 8; kv[c] = *(const u32x4*)p; vv[c] = *(const u32x4*)(p + HD); }
; }
; template <int T0, int NT, bool FIRST>
; __device__ __forceinline__ void attn_group(LAS const unsigned char* Kl, LAS const unsigned char* Vl, const bf16x8 (&qf)[4], f32x16 (&o)[2], float& mx, float& l, int nb, int w, int lane) {
;     const int r32 = lane & 31, hi = lane >> 5;
;     f32x16 s[NT];
; #pragma unroll
;     for (int t = 0; t < NT; ++t) { const float z = (T0 + t < 4 && nb == 0 && w + T0 + t < 4) ? NEGBIG : 0.f;
;         s[t] = (f32x16){z, z, z, z, z, z, z, z, z, z, z, z, z, z, z, z}; }
;     {
;         LAS const unsigned char* kp = Kl + (32 * (w + T0) + r32) * 128;
;         const int sw = (r32 >> 1) & 7;
; #pragma unroll
;         for (int ks = 0; ks < 4; ++ks) {
;             bf16x8 kf[NT];
; #pragma unroll
;             for (int t = 0; t < NT; ++t) kf[t] = *(LAS const bf16x8*)(kp + t * 4096 + (((2 * ks + hi) ^ sw) * 16));
; #pragma unroll
;             for (int t = 0; t < NT; ++t) s[t] = __builtin_amdgcn_mfma_f32_32x32x16_bf16(kf[t], qf[ks], s[t], 0, 0, 0);
;         }
.LBB0_112:
	s_lshl_b32 s2, s7, 1
	s_ashr_i32 s48, s19, 11
	s_add_i32 s19, s2, s18
	s_and_b32 s6, s19, 63
	s_cmpk_lt_u32 s19, 0x800
	s_cselect_b64 s[46:47], -1, 0
	s_and_b64 s[2:3], s[46:47], exec
	s_cselect_b32 s7, 15, 3
	s_cselect_b32 s2, 4, 2
	s_cselect_b32 s3, 2, 4
	s_and_b32 s15, s7, s19
	s_lshl_b32 s49, s15, 7
	s_lshr_b32 s98, s6, s2
	s_and_b32 s6, s49, 0x700
	s_add_i32 s7, s6, 0xffffff80
	v_add_u32_e32 v2, s7, v132
	v_add_u32_e32 v3, s6, v132
	v_cmp_gt_i32_e32 vcc, 0, v2
	s_bfe_u32 s99, s19, 0x20009
	s_bfe_u32 s11, s19, 0x30006
	v_cndmask_b32_e32 v2, v2, v3, vcc
	v_lshlrev_b32_e32 v2, s3, v2
	v_add_u32_e32 v2, s98, v2
	v_lshlrev_b32_e32 v4, 7, v2
	s_lshl_b32 s2, s99, 3
	v_and_b32_e32 v3, 0xfffff800, v2
	v_and_b32_e32 v4, 0x780, v4
	v_bfe_u32 v2, v2, 4, 7
	s_or_b32 s2, s2, s11
	v_or3_b32 v2, v4, v3, v2
	s_lshl_b32 s12, s2, 21
	v_ashrrev_i32_e32 v3, 31, v2
	v_lshl_add_u64 v[0:1], v[130:131], 0, s[12:13]
	v_lshlrev_b64 v[2:3], 8, v[2:3]
	v_lshl_add_u64 v[2:3], v[0:1], 0, v[2:3]
	global_load_dwordx4 v[64:67], v[2:3], off
	global_load_dwordx4 v[68:71], v[2:3], off offset:128
	v_add_u32_e32 v2, s7, v133
	v_add_u32_e32 v3, s6, v133
	v_cmp_gt_i32_e32 vcc, 0, v2
	s_cmp_eq_u32 s25, 0
	v_add_u32_e32 v40, v138, v139
	v_cndmask_b32_e32 v2, v2, v3, vcc
	v_lshlrev_b32_e32 v2, s3, v2
	v_add_u32_e32 v2, s98, v2
	v_lshlrev_b32_e32 v4, 7, v2
	v_and_b32_e32 v3, 0xfffff800, v2
	v_and_b32_e32 v4, 0x780, v4
	v_bfe_u32 v2, v2, 4, 7
	v_or3_b32 v2, v4, v3, v2
	v_ashrrev_i32_e32 v3, 31, v2
	v_lshlrev_b64 v[2:3], 8, v[2:3]
	v_lshl_add_u64 v[2:3], v[0:1], 0, v[2:3]
	global_load_dwordx4 v[72:75], v[2:3], off
	global_load_dwordx4 v[76:79], v[2:3], off offset:128
	v_add_u32_e32 v2, s7, v134
	v_add_u32_e32 v3, s6, v134
	v_cmp_gt_i32_e32 vcc, 0, v2
	v_add_u32_e32 v56, v138, v140
	v_add_u32_e32 v196, v143, v144
	v_cndmask_b32_e32 v2, v2, v3, vcc
	v_lshlrev_b32_e32 v2, s3, v2
	v_add_u32_e32 v2, s98, v2
	v_lshlrev_b32_e32 v4, 7, v2
	v_and_b32_e32 v3, 0xfffff800, v2
	v_and_b32_e32 v4, 0x780, v4
	v_bfe_u32 v2, v2, 4, 7
	v_or3_b32 v2, v4, v3, v2
	v_ashrrev_i32_e32 v3, 31, v2
	v_lshlrev_b64 v[2:3], 8, v[2:3]
	v_lshl_add_u64 v[2:3], v[0:1], 0, v[2:3]
	global_load_dwordx4 v[80:83], v[2:3], off
	global_load_dwordx4 v[84:87], v[2:3], off offset:128
	v_add_u32_e32 v2, s7, v135
	v_add_u32_e32 v3, s6, v135
	v_cmp_gt_i32_e32 vcc, 0, v2
	v_add_u32_e32 v197, v143, v145
	s_nop 0
	v_cndmask_b32_e32 v2, v2, v3, vcc
	v_lshlrev_b32_e32 v2, s3, v2
	v_add_u32_e32 v2, s98, v2
	v_lshlrev_b32_e32 v4, 7, v2
	v_and_b32_e32 v3, 0xfffff800, v2
	v_and_b32_e32 v4, 0x780, v4
	v_bfe_u32 v2, v2, 4, 7
	v_or3_b32 v2, v4, v3, v2
	v_ashrrev_i32_e32 v3, 31, v2
	v_lshlrev_b64 v[2:3], 8, v[2:3]
	v_lshl_add_u64 v[2:3], v[0:1], 0, v[2:3]
	global_load_dwordx4 v[88:91], v[2:3], off
	global_load_dwordx4 v[92:95], v[2:3], off offset:128
	v_add_u32_e32 v2, s7, v136
	v_add_u32_e32 v3, s6, v136
	v_cmp_gt_i32_e32 vcc, 0, v2
	s_nop 1
	v_cndmask_b32_e32 v2, v2, v3, vcc
	v_lshlrev_b32_e32 v2, s3, v2
	v_add_u32_e32 v2, s98, v2
	v_lshlrev_b32_e32 v4, 7, v2
	v_and_b32_e32 v3, 0xfffff800, v2
	v_and_b32_e32 v4, 0x780, v4
	v_bfe_u32 v2, v2, 4, 7
	v_or3_b32 v2, v4, v3, v2
	v_ashrrev_i32_e32 v3, 31, v2
	v_lshlrev_b64 v[2:3], 8, v[2:3]
	v_lshl_add_u64 v[2:3], v[0:1], 0, v[2:3]
	global_load_dwordx4 v[96:99], v[2:3], off
	global_load_dwordx4 v[100:103], v[2:3], off offset:128
	v_add_u32_e32 v2, s7, v137
	v_add_u32_e32 v3, s6, v137
	v_cmp_gt_i32_e32 vcc, 0, v2
	s_cselect_b64 s[6:7], -1, 0
	s_or_b32 s10, s25, s26
	v_cndmask_b32_e32 v2, v2, v3, vcc
	v_lshlrev_b32_e32 v2, s3, v2
	v_add_u32_e32 v2, s98, v2
	v_lshlrev_b32_e32 v4, 7, v2
	v_and_b32_e32 v3, 0xfffff800, v2
	v_and_b32_e32 v4, 0x780, v4
	v_bfe_u32 v2, v2, 4, 7
	v_or3_b32 v2, v4, v3, v2
	v_ashrrev_i32_e32 v3, 31, v2
	v_lshlrev_b64 v[2:3], 8, v[2:3]
	v_readlane_b32 vcc_lo, v250, 4
	v_lshl_add_u64 v[0:1], v[0:1], 0, v[2:3]
	v_readlane_b32 vcc_hi, v250, 5
	global_load_dwordx4 v[104:107], v[0:1], off
	global_load_dwordx4 v[108:111], v[0:1], off offset:128
	s_and_b64 vcc, s[6:7], vcc
	ds_read_b128 v[32:35], v40
	ds_read_b128 v[36:39], v40 offset:4096
	ds_read_b128 v[40:43], v40 offset:8192
	s_cmp_eq_u32 s10, 0
	v_cndmask_b32_e32 v16, 0, v227, vcc
	s_cselect_b64 vcc, -1, 0
	v_cndmask_b32_e32 v0, 0, v227, vcc
	v_mov_b32_e32 v17, v16
	v_mov_b32_e32 v18, v16
	v_mov_b32_e32 v19, v16
	v_mov_b32_e32 v20, v16
	v_mov_b32_e32 v21, v16
	v_mov_b32_e32 v22, v16
	v_mov_b32_e32 v23, v16
	v_mov_b32_e32 v24, v16
	v_mov_b32_e32 v25, v16
	v_mov_b32_e32 v26, v16
	v_mov_b32_e32 v27, v16
	v_mov_b32_e32 v28, v16
	v_mov_b32_e32 v29, v16
	v_mov_b32_e32 v30, v16
	v_mov_b32_e32 v31, v16
	v_mov_b32_e32 v1, v0
	v_mov_b32_e32 v2, v0
	v_mov_b32_e32 v3, v0
	v_mov_b32_e32 v4, v0
	v_mov_b32_e32 v5, v0
	v_mov_b32_e32 v6, v0
	v_mov_b32_e32 v7, v0
	v_mov_b32_e32 v8, v0
	v_mov_b32_e32 v9, v0
	v_mov_b32_e32 v10, v0
	v_mov_b32_e32 v11, v0
	v_mov_b32_e32 v12, v0
	v_mov_b32_e32 v13, v0
	v_mov_b32_e32 v14, v0
	v_mov_b32_e32 v15, v0
	s_waitcnt vmcnt(15) lgkmcnt(2)
	v_mfma_f32_32x32x16_bf16 v[16:31], v[32:35], v[124:127], v[16:31]
	ds_read_b128 v[48:51], v56
	ds_read_b128 v[52:55], v56 offset:4096
	ds_read_b128 v[56:59], v56 offset:8192
	v_readlane_b32 vcc_lo, v250, 6
	v_readlane_b32 vcc_hi, v250, 7
	s_lshl_b32 s2, s2, 20
	s_waitcnt lgkmcnt(4)
	v_mfma_f32_32x32x16_bf16 v[0:15], v[36:39], v[124:127], v[0:15]
	s_waitcnt lgkmcnt(3)
	v_mfma_f32_32x32x16_bf16 v[32:47], v[40:43], v[124:127], 0
	s_waitcnt vmcnt(14) lgkmcnt(0)
	v_mfma_f32_32x32x16_bf16 v[32:47], v[56:59], v[120:123], v[32:47]
	v_add_u32_e32 v56, v138, v141
	v_mfma_f32_32x32x16_bf16 v[16:31], v[48:51], v[120:123], v[16:31]
	v_mfma_f32_32x32x16_bf16 v[0:15], v[52:55], v[120:123], v[0:15]
	ds_read_b128 v[48:51], v56
	ds_read_b128 v[52:55], v56 offset:4096
	ds_read_b128 v[56:59], v56 offset:8192
	s_waitcnt vmcnt(13) lgkmcnt(0)
; #define LAS __attribute__((address_space(3)))
; __device__ __forceinline__ int crow(int i, int hi) { return (i & 3) + 8 * (i >> 2) + 4 * hi; }
; template <int T0, int NT, bool FIRST>
; __device__ __forceinline__ void attn_group(LAS const unsigned char* Kl, LAS const unsigned char* Vl, const bf16x8 (&qf)[4], f32x16 (&o)[2], float& mx, float& l, int nb, int w, int lane) {
;     ...
;         for (int ks = 0; ks < 4; ++ks) {
;             bf16x8 kf[NT];
; #pragma unroll
;             for (int t = 0; t < NT; ++t) kf[t] = *(LAS const bf16x8*)(kp + t * 4096 + (((2 * ks + hi) ^ sw) * 16));
; #pragma unroll
;             for (int t = 0; t < NT; ++t) s[t] = __builtin_amdgcn_mfma_f32_32x32x16_bf16(kf[t], qf[ks], s[t], 0, 0, 0);
;         }
;     }
; #pragma unroll
;     for (int t = 0; t < NT; ++t) {
;         const int tt = T0 + t;
;         if (tt == 0) {
; #pragma unroll
;             for (int i = 0; i < 16; ++i) if (crow(i, hi) < r32) s[t][i] = NEGBIG; }
;         if (tt == 4) {
; #pragma unroll
;             for (int i = 0; i < 16; ++i) if (crow(i, hi) > r32) s[t][i] = NEGBIG; }
;     }
;     float m0 = s[0][0], m1 = s[0][1], m2 = s[0][2], m3 = s[0][3];
; #pragma unroll
;     for (int t = 0; t < NT; ++t)
; #pragma unroll
;         for (int i = 0; i < 16; i += 4) { m0 = fmaxf(m0, s[t][i]); m1 = fmaxf(m1, s[t][i + 1]); m2 = fmaxf(m2, s[t][i + 2]); m3 = fmaxf(m3, s[t][i + 3]); }
;     float gm = fmaxf(fmaxf(m0, m1), fmaxf(m2, m3));
;     gm = fmaxf(gm, __shfl_xor(gm, 32));
;     if (FIRST) mx = gm;
;     else { const float mn = fmaxf(mx, gm); const float f = __builtin_amdgcn_exp2f(mx - mn); l *= f; mx = mn;
; #pragma unroll
;         for (int d = 0; d < 2; ++d)
; #pragma unroll
;             for (int i = 0; i < 16; ++i) o[d][i] *= f; }
;     float l0 = 0.f, l1 = 0.f, l2 = 0.f, l3 = 0.f;
; #pragma unroll
;     for (int t = 0; t < NT; ++t)
; #pragma unroll
;         for (int i = 0; i < 16; i += 4) {
;             const float p0 = __builtin_amdgcn_exp2f(s[t][i] - mx), p1 = __builtin_amdgcn_exp2f(s[t][i + 1] - mx), p2 = __builtin_amdgcn_exp2f(s[t][i + 2] - mx), p3 = __builtin_amdgcn_exp2f(s[t][i + 3] - mx);
;             s[t][i] = p0; s[t][i + 1] = p1; s[t][i + 2] = p2; s[t][i + 3] = p3; l0 += p0; l1 += p1; l2 += p2; l3 += p3; }
	v_mfma_f32_32x32x16_bf16 v[32:47], v[56:59], v[116:119], v[32:47]
	v_add_u32_e32 v56, v138, v142
	v_mfma_f32_32x32x16_bf16 v[16:31], v[48:51], v[116:119], v[16:31]
	v_mfma_f32_32x32x16_bf16 v[0:15], v[52:55], v[116:119], v[0:15]
	ds_read_b128 v[48:51], v56
	ds_read_b128 v[52:55], v56 offset:4096
	ds_read_b128 v[56:59], v56 offset:8192
	s_waitcnt vmcnt(12) lgkmcnt(0)
	v_mfma_f32_32x32x16_bf16 v[32:47], v[56:59], v[112:115], v[32:47]
	v_mfma_f32_32x32x16_bf16 v[16:31], v[48:51], v[112:115], v[16:31]
	s_nop 10
	v_cndmask_b32_e32 v48, v32, v227, vcc
	v_readlane_b32 vcc_lo, v250, 8
	v_readlane_b32 vcc_hi, v250, 9
	v_cndmask_b32_e64 v32, v48, v32, s[40:41]
	v_cndmask_b32_e64 v33, v227, v33, s[40:41]
	v_cndmask_b32_e32 v34, v34, v227, vcc
	v_readlane_b32 vcc_lo, v250, 10
	v_readlane_b32 vcc_hi, v250, 11
	v_mfma_f32_32x32x16_bf16 v[0:15], v[52:55], v[112:115], v[0:15]
	v_max_f32_e32 v48, v20, v20
	v_cndmask_b32_e32 v35, v35, v227, vcc
	v_readlane_b32 vcc_lo, v250, 12
	v_readlane_b32 vcc_hi, v250, 13
	v_max_f32_e32 v49, v16, v16
	v_max_f32_e32 v48, v49, v48
	v_cndmask_b32_e32 v36, v36, v227, vcc
	v_readlane_b32 vcc_lo, v250, 14
	v_readlane_b32 vcc_hi, v250, 15
	v_max_f32_e32 v49, v21, v21
	v_max_f32_e32 v50, v17, v17
	v_cndmask_b32_e32 v37, v37, v227, vcc
	v_readlane_b32 vcc_lo, v250, 16
	v_readlane_b32 vcc_hi, v250, 17
	v_max_f32_e32 v49, v50, v49
	v_max_f32_e32 v50, v23, v23
	v_cndmask_b32_e32 v38, v38, v227, vcc
	v_readlane_b32 vcc_lo, v250, 18
	v_readlane_b32 vcc_hi, v250, 19
	v_max_f32_e32 v51, v19, v19
	v_max_f32_e32 v50, v51, v50
	v_cndmask_b32_e32 v39, v39, v227, vcc
	v_readlane_b32 vcc_lo, v250, 20
	v_readlane_b32 vcc_hi, v250, 21
	v_max3_f32 v51, v18, v22, v26
	v_max3_f32 v50, v50, v27, v31
	v_cndmask_b32_e32 v40, v40, v227, vcc
	v_readlane_b32 vcc_lo, v250, 22
	v_readlane_b32 vcc_hi, v250, 23
	v_max3_f32 v48, v48, v24, v28
	v_max3_f32 v49, v49, v25, v29
	v_cndmask_b32_e32 v41, v41, v227, vcc
	v_readlane_b32 vcc_lo, v250, 24
	v_readlane_b32 vcc_hi, v250, 25
	v_max3_f32 v51, v51, v30, v2
	v_max3_f32 v50, v50, v3, v7
	v_cndmask_b32_e32 v42, v42, v227, vcc
	v_readlane_b32 vcc_lo, v250, 26
	v_readlane_b32 vcc_hi, v250, 27
	v_max3_f32 v48, v48, v0, v4
	v_max3_f32 v49, v49, v1, v5
	v_cndmask_b32_e32 v43, v43, v227, vcc
	v_readlane_b32 vcc_lo, v250, 28
	v_max3_f32 v51, v51, v6, v10
	v_max3_f32 v50, v50, v11, v15
	v_readlane_b32 vcc_hi, v250, 29
	v_cndmask_b32_e64 v47, v47, v227, s[68:69]
	v_max3_f32 v48, v48, v8, v12
	v_max3_f32 v49, v49, v9, v13
	v_max3_f32 v51, v51, v14, v34
	v_max3_f32 v50, v50, v35, v39
	v_cndmask_b32_e32 v44, v44, v227, vcc
	v_cndmask_b32_e64 v45, v45, v227, s[64:65]
	v_cndmask_b32_e64 v46, v46, v227, s[66:67]
	v_max3_f32 v48, v48, v32, v36
	v_max3_f32 v49, v49, v33, v37
	v_max3_f32 v51, v51, v38, v42
	v_max3_f32 v50, v50, v43, v47
	v_max3_f32 v48, v48, v40, v44
	v_max3_f32 v49, v49, v41, v45
	v_max3_f32 v50, v51, v46, v50
	v_max3_f32 v48, v48, v49, v50
	v_mov_b32_e32 v49, v48
	s_nop 1
	v_permlane32_swap_b32_e32 v49, v48
	s_waitcnt lgkmcnt(0)
	v_max_f32_e32 v49, v49, v49
	v_max_f32_e32 v163, v48, v49
	v_sub_f32_e32 v4, v4, v163
	v_exp_f32_e32 v60, v4
	v_sub_f32_e32 v4, v5, v163
	v_exp_f32_e32 v61, v4
	v_sub_f32_e32 v4, v6, v163
	v_exp_f32_e32 v62, v4
	v_sub_f32_e32 v4, v7, v163
	v_exp_f32_e32 v63, v4
	v_sub_f32_e32 v4, v8, v163
	v_exp_f32_e32 v165, v4
	v_sub_f32_e32 v4, v9, v163
	v_exp_f32_e32 v166, v4
	v_sub_f32_e32 v4, v10, v163
	v_exp_f32_e32 v167, v4
	v_sub_f32_e32 v4, v11, v163
	v_exp_f32_e32 v168, v4
	v_sub_f32_e32 v4, v12, v163
	v_exp_f32_e32 v183, v4
	v_sub_f32_e32 v4, v13, v163
	v_sub_f32_e32 v16, v16, v163
	v_exp_f32_e32 v185, v4
	v_sub_f32_e32 v4, v14, v163
	v_exp_f32_e32 v16, v16
	v_sub_f32_e32 v17, v17, v163
	v_sub_f32_e32 v20, v20, v163
	v_exp_f32_e32 v186, v4
	v_sub_f32_e32 v4, v15, v163
	v_exp_f32_e32 v17, v17
	v_sub_f32_e32 v18, v18, v163
	v_exp_f32_e32 v20, v20
	v_sub_f32_e32 v21, v21, v163
	v_sub_f32_e32 v24, v24, v163
	v_exp_f32_e32 v187, v4
	v_sub_f32_e32 v4, v32, v163
	v_exp_f32_e32 v18, v18
	v_sub_f32_e32 v19, v19, v163
	v_exp_f32_e32 v21, v21
	v_sub_f32_e32 v22, v22, v163
	v_exp_f32_e32 v52, v24
	v_sub_f32_e32 v24, v25, v163
	v_exp_f32_e32 v188, v4
	v_sub_f32_e32 v4, v33, v163
	v_exp_f32_e32 v19, v19
	v_exp_f32_e32 v22, v22
	v_sub_f32_e32 v23, v23, v163
	v_exp_f32_e32 v53, v24
	v_sub_f32_e32 v24, v26, v163
	v_exp_f32_e32 v189, v4
	v_sub_f32_e32 v4, v34, v163
	v_add_f32_e32 v48, 0, v16
	v_exp_f32_e32 v23, v23
	v_exp_f32_e32 v54, v24
	v_sub_f32_e32 v24, v27, v163
	v_exp_f32_e32 v190, v4
	v_sub_f32_e32 v4, v35, v163
	v_add_f32_e32 v49, 0, v17
	v_add_f32_e32 v48, v20, v48
	v_exp_f32_e32 v55, v24
	v_sub_f32_e32 v28, v28, v163
	v_exp_f32_e32 v191, v4
	v_sub_f32_e32 v4, v36, v163
	v_add_f32_e32 v50, 0, v18
	v_add_f32_e32 v49, v21, v49
	v_add_f32_e32 v24, v52, v48
	v_exp_f32_e32 v48, v28
	v_sub_f32_e32 v28, v29, v163
	v_sub_f32_e32 v0, v0, v163
	v_exp_f32_e32 v192, v4
	v_sub_f32_e32 v4, v37, v163
	v_add_f32_e32 v51, 0, v19
	v_add_f32_e32 v50, v22, v50
	v_add_f32_e32 v25, v53, v49
	v_exp_f32_e32 v49, v28
	v_sub_f32_e32 v28, v30, v163
	v_exp_f32_e32 v56, v0
	v_sub_f32_e32 v0, v1, v163
	v_exp_f32_e32 v193, v4
	v_sub_f32_e32 v4, v38, v163
	v_add_f32_e32 v51, v23, v51
	v_add_f32_e32 v26, v54, v50
	v_exp_f32_e32 v50, v28
	v_sub_f32_e32 v28, v31, v163
	v_exp_f32_e32 v57, v0
	v_sub_f32_e32 v0, v2, v163
	v_exp_f32_e32 v194, v4
	v_sub_f32_e32 v4, v39, v163
	v_add_f32_e32 v27, v55, v51
	v_exp_f32_e32 v51, v28
	v_exp_f32_e32 v58, v0
	v_sub_f32_e32 v0, v3, v163
	v_exp_f32_e32 v195, v4
	v_sub_f32_e32 v4, v40, v163
	v_exp_f32_e32 v59, v0
	v_exp_f32_e32 v40, v4
	v_sub_f32_e32 v4, v41, v163
	v_exp_f32_e32 v41, v4
; #define LAS __attribute__((address_space(3)))
; template <int T0, int NT, bool FIRST>
; __device__ __forceinline__ void attn_group(LAS const unsigned char* Kl, LAS const unsigned char* Vl, const bf16x8 (&qf)[4], f32x16 (&o)[2], float& mx, float& l, int nb, int w, int lane) {
;     ...
;     f32x16 s[NT];
; #pragma unroll
;     for (int t = 0; t < NT; ++t) { const float z = (T0 + t < 4 && nb == 0 && w + T0 + t < 4) ? NEGBIG : 0.f;
;         s[t] = (f32x16){z, z, z, z, z, z, z, z, z, z, z, z, z, z, z, z}; }
;     {
;         LAS const unsigned char* kp = Kl + (32 * (w + T0) + r32) * 128;
;         const int sw = (r32 >> 1) & 7;
; #pragma unroll
;         for (int ks = 0; ks < 4; ++ks) {
;             bf16x8 kf[NT];
; #pragma unroll
;     ...
;     float l0 = 0.f, l1 = 0.f, l2 = 0.f, l3 = 0.f;
; #pragma unroll
;     for (int t = 0; t < NT; ++t)
; #pragma unroll
;         for (int i = 0; i < 16; i += 4) {
;             const float p0 = __builtin_amdgcn_exp2f(s[t][i] - mx), p1 = __builtin_amdgcn_exp2f(s[t][i + 1] - mx), p2 = __builtin_amdgcn_exp2f(s[t][i + 2] - mx), p3 = __builtin_amdgcn_exp2f(s[t][i + 3] - mx);
;             s[t][i] = p0; s[t][i + 1] = p1; s[t][i + 2] = p2; s[t][i + 3] = p3; l0 += p0; l1 += p1; l2 += p2; l3 += p3; }
;     l += (l0 + l1) + (l2 + l3);
;     const int i16 = lane & 15, q4 = i16 >> 2, p4 = i16 & 3, blk = (lane >> 4) & 1;
;     LAS const unsigned char* vb = Vl + (32 * (w + T0) + 4 * hi + q4) * 128 + 32 * blk + 8 * p4;
;     const int vsw = ((q4 >> 1) & 1) * 64;
; #pragma unroll
;     for (int t = 0; t < NT; ++t)
; #pragma unroll
;         for (int s2 = 0; s2 < 2; ++s2) {
;             u32x4 pw; pw.x = cvt_pk_bf16(s[t][8 * s2 + 0], s[t][8 * s2 + 1]); pw.y = cvt_pk_bf16(s[t][8 * s2 + 2], s[t][8 * s2 + 3]);
;             pw.z = cvt_pk_bf16(s[t][8 * s2 + 4], s[t][8 * s2 + 5]); pw.w = cvt_pk_bf16(s[t][8 * s2 + 6], s[t][8 * s2 + 7]);
;             const bf16x8 pf = __builtin_bit_cast(bf16x8, pw);
; #pragma unroll
;             for (int d = 0; d < 2; ++d) {
;                 LAS const unsigned char* vp = vb + (t * 32 + s2 * 16) * 128 + ((d * 64) ^ vsw);
;                 const s16x4 lo = vtr(vp), hi4 = vtr(vp + 8 * 128);
;                 const bf16x8 vf = (bf16x8){lo[0], lo[1], lo[2], lo[3], hi4[0], hi4[1], hi4[2], hi4[3]};
;                 o[d] = __builtin_amdgcn_mfma_f32_32x32x16_bf16(vf, pf, o[d], 0, 0, 0);
;             }
;         }
; }
	v_sub_f32_e32 v4, v42, v163
	v_exp_f32_e32 v42, v4
	v_sub_f32_e32 v4, v43, v163
	v_add_f32_e32 v24, v48, v24
	v_add_f32_e32 v25, v49, v25
	v_add_f32_e32 v26, v50, v26
	v_add_f32_e32 v27, v51, v27
	v_exp_f32_e32 v43, v4
	v_sub_f32_e32 v4, v44, v163
	v_add_f32_e32 v0, v56, v24
	v_add_f32_e32 v1, v57, v25
	v_add_f32_e32 v2, v58, v26
	v_add_f32_e32 v3, v59, v27
	v_exp_f32_e32 v44, v4
	v_sub_f32_e32 v4, v45, v163
	v_add_f32_e32 v0, v60, v0
	v_add_f32_e32 v1, v61, v1
	v_add_f32_e32 v2, v62, v2
	v_add_f32_e32 v3, v63, v3
	v_exp_f32_e32 v45, v4
	v_sub_f32_e32 v4, v46, v163
	v_add_f32_e32 v0, v165, v0
	v_add_f32_e32 v1, v166, v1
	v_add_f32_e32 v2, v167, v2
	v_add_f32_e32 v3, v168, v3
	v_exp_f32_e32 v46, v4
	v_sub_f32_e32 v4, v47, v163
	v_add_f32_e32 v0, v183, v0
	v_add_f32_e32 v1, v185, v1
	v_add_f32_e32 v2, v186, v2
	v_add_f32_e32 v3, v187, v3
	v_exp_f32_e32 v47, v4
	v_add_f32_e32 v0, v188, v0
	v_add_f32_e32 v1, v189, v1
	v_add_f32_e32 v2, v190, v2
	v_add_f32_e32 v3, v191, v3
	v_add_f32_e32 v0, v192, v0
	v_add_f32_e32 v1, v193, v1
	v_add_f32_e32 v2, v194, v2
	v_add_f32_e32 v3, v195, v3
	v_add_f32_e32 v0, v40, v0
	v_add_f32_e32 v1, v41, v1
	v_add_f32_e32 v2, v42, v2
	v_add_f32_e32 v3, v43, v3
	ds_read_b64_tr_b16 v[4:5], v196 offset:49152
	ds_read_b64_tr_b16 v[6:7], v196 offset:50176
	v_add_f32_e32 v0, v44, v0
	v_add_f32_e32 v1, v45, v1
	v_add_f32_e32 v2, v46, v2
	v_add_f32_e32 v3, v47, v3
	v_add_f32_e32 v0, v1, v0
	v_add_f32_e32 v1, v2, v3
	v_add_f32_e32 v0, v1, v0
	v_add_f32_e32 v164, 0, v0
	v_cvt_pk_bf16_f32 v0, v16, v17
	v_cvt_pk_bf16_f32 v1, v18, v19
	v_cvt_pk_bf16_f32 v2, v20, v21
	v_cvt_pk_bf16_f32 v3, v22, v23
	v_cvt_pk_bf16_f32 v32, v52, v53
	v_cvt_pk_bf16_f32 v33, v54, v55
	s_waitcnt lgkmcnt(0)
	v_mfma_f32_32x32x16_bf16 v[16:31], v[4:7], v[0:3], 0
	ds_read_b64_tr_b16 v[4:5], v197 offset:49152
	ds_read_b64_tr_b16 v[6:7], v197 offset:50176
	ds_read_b64_tr_b16 v[36:37], v196 offset:51200
	ds_read_b64_tr_b16 v[38:39], v196 offset:52224
	v_cvt_pk_bf16_f32 v34, v48, v49
	v_cvt_pk_bf16_f32 v35, v50, v51
	s_waitcnt lgkmcnt(2)
	v_mfma_f32_32x32x16_bf16 v[0:15], v[4:7], v[0:3], 0
	s_waitcnt lgkmcnt(0)
	v_mfma_f32_32x32x16_bf16 v[16:31], v[36:39], v[32:35], v[16:31]
	ds_read_b64_tr_b16 v[36:37], v197 offset:51200
	ds_read_b64_tr_b16 v[38:39], v197 offset:52224
	s_waitcnt lgkmcnt(0)
	v_mfma_f32_32x32x16_bf16 v[0:15], v[36:39], v[32:35], v[0:15]
	ds_read_b64_tr_b16 v[36:37], v196 offset:53248
	ds_read_b64_tr_b16 v[38:39], v196 offset:54272
	ds_read_b64_tr_b16 v[198:199], v197 offset:53248
	ds_read_b64_tr_b16 v[200:201], v197 offset:54272
	v_cvt_pk_bf16_f32 v32, v56, v57
	v_cvt_pk_bf16_f32 v33, v58, v59
	v_cvt_pk_bf16_f32 v34, v60, v61
	v_cvt_pk_bf16_f32 v35, v62, v63
	s_waitcnt lgkmcnt(2)
	s_nop 0
	v_mfma_f32_32x32x16_bf16 v[16:31], v[36:39], v[32:35], v[16:31]
	s_waitcnt lgkmcnt(0)
	v_mfma_f32_32x32x16_bf16 v[0:15], v[198:201], v[32:35], v[0:15]
	ds_read_b64_tr_b16 v[36:37], v196 offset:55296
	ds_read_b64_tr_b16 v[38:39], v196 offset:56320
	ds_read_b64_tr_b16 v[198:199], v197 offset:55296
	ds_read_b64_tr_b16 v[200:201], v197 offset:56320
	v_cvt_pk_bf16_f32 v32, v165, v166
	v_cvt_pk_bf16_f32 v33, v167, v168
	v_cvt_pk_bf16_f32 v34, v183, v185
	v_cvt_pk_bf16_f32 v35, v186, v187
	v_add_u32_e32 v165, v147, v140
	s_waitcnt lgkmcnt(2)
	v_mfma_f32_32x32x16_bf16 v[16:31], v[36:39], v[32:35], v[16:31]
	s_waitcnt lgkmcnt(0)
	v_mfma_f32_32x32x16_bf16 v[0:15], v[198:201], v[32:35], v[0:15]
	ds_read_b64_tr_b16 v[36:37], v196 offset:57344
	ds_read_b64_tr_b16 v[38:39], v196 offset:58368
	ds_read_b64_tr_b16 v[198:199], v197 offset:57344
	ds_read_b64_tr_b16 v[200:201], v197 offset:58368
	v_cvt_pk_bf16_f32 v32, v188, v189
	v_cvt_pk_bf16_f32 v33, v190, v191
	v_cvt_pk_bf16_f32 v34, v192, v193
	v_cvt_pk_bf16_f32 v35, v194, v195
	s_waitcnt lgkmcnt(2)
	s_nop 0
	v_mfma_f32_32x32x16_bf16 v[16:31], v[36:39], v[32:35], v[16:31]
	s_waitcnt lgkmcnt(0)
	v_mfma_f32_32x32x16_bf16 v[0:15], v[198:201], v[32:35], v[0:15]
	ds_read_b64_tr_b16 v[36:37], v196 offset:59392
	ds_read_b64_tr_b16 v[38:39], v196 offset:60416
	ds_read_b64_tr_b16 v[198:199], v197 offset:59392
	ds_read_b64_tr_b16 v[200:201], v197 offset:60416
	v_cvt_pk_bf16_f32 v32, v40, v41
	v_cvt_pk_bf16_f32 v33, v42, v43
	v_cvt_pk_bf16_f32 v34, v44, v45
	v_cvt_pk_bf16_f32 v35, v46, v47
	s_waitcnt lgkmcnt(2)
	s_nop 0
	v_mfma_f32_32x32x16_bf16 v[16:31], v[36:39], v[32:35], v[16:31]
	s_waitcnt lgkmcnt(0)
	v_mfma_f32_32x32x16_bf16 v[0:15], v[198:201], v[32:35], v[0:15]
	v_add_u32_e32 v33, v147, v139
	ds_read_b128 v[50:53], v33
	ds_read_b128 v[186:189], v33 offset:4096
	v_cndmask_b32_e64 v32, 0, v227, s[6:7]
	v_mov_b32_e32 v33, v32
	v_mov_b32_e32 v34, v32
	v_mov_b32_e32 v35, v32
	v_mov_b32_e32 v36, v32
	v_mov_b32_e32 v37, v32
	v_mov_b32_e32 v38, v32
	v_mov_b32_e32 v39, v32
	v_mov_b32_e32 v40, v32
	v_mov_b32_e32 v41, v32
	v_mov_b32_e32 v42, v32
	v_mov_b32_e32 v43, v32
	v_mov_b32_e32 v44, v32
	v_mov_b32_e32 v45, v32
	v_mov_b32_e32 v46, v32
	v_mov_b32_e32 v47, v32
	v_cndmask_b32_e64 v48, 0, v32, s[70:71]
	v_mov_b32_e32 v49, v48
	s_waitcnt lgkmcnt(1)
	v_mfma_f32_32x32x16_bf16 v[32:47], v[50:53], v[124:127], v[32:47]
	v_mov_b32_e32 v50, v48
	v_mov_b32_e32 v51, v48
	v_mov_b32_e32 v52, v48
	v_mov_b32_e32 v53, v48
	v_mov_b32_e32 v54, v48
	v_mov_b32_e32 v55, v48
	v_mov_b32_e32 v56, v48
	v_mov_b32_e32 v57, v48
	v_mov_b32_e32 v58, v48
	v_mov_b32_e32 v59, v48
	v_mov_b32_e32 v60, v48
	v_mov_b32_e32 v61, v48
	v_mov_b32_e32 v62, v48
	v_mov_b32_e32 v63, v48
	v_readlane_b32 s6, v251, 59
	v_readlane_b32 s7, v251, 60
	s_waitcnt lgkmcnt(0)
	v_mfma_f32_32x32x16_bf16 v[48:63], v[186:189], v[124:127], v[48:63]
	ds_read_b128 v[124:127], v165
	ds_read_b128 v[186:189], v165 offset:4096
	s_add_u32 s2, s6, s2
	s_waitcnt lgkmcnt(1)
; __device__ __forceinline__ int crow(int i, int hi) { return (i & 3) + 8 * (i >> 2) + 4 * hi; }
; template <int T0, int NT, bool FIRST>
; __device__ __forceinline__ void attn_group(LAS const unsigned char* Kl, LAS const unsigned char* Vl, const bf16x8 (&qf)[4], f32x16 (&o)[2], float& mx, float& l, int nb, int w, int lane) {
;     ...
; #pragma unroll
;     for (int t = 0; t < NT; ++t) {
;         const int tt = T0 + t;
;         if (tt == 0) {
; #pragma unroll
;             for (int i = 0; i < 16; ++i) if (crow(i, hi) < r32) s[t][i] = NEGBIG; }
;         if (tt == 4) {
; #pragma unroll
;             for (int i = 0; i < 16; ++i) if (crow(i, hi) > r32) s[t][i] = NEGBIG; }
;     }
;     float m0 = s[0][0], m1 = s[0][1], m2 = s[0][2], m3 = s[0][3];
; #pragma unroll
;     for (int t = 0; t < NT; ++t)
; #pragma unroll
;         for (int i = 0; i < 16; i += 4) { m0 = fmaxf(m0, s[t][i]); m1 = fmaxf(m1, s[t][i + 1]); m2 = fmaxf(m2, s[t][i + 2]); m3 = fmaxf(m3, s[t][i + 3]); }
;     float gm = fmaxf(fmaxf(m0, m1), fmaxf(m2, m3));
;     gm = fmaxf(gm, __shfl_xor(gm, 32));
;     if (FIRST) mx = gm;
;     else { const float mn = fmaxf(mx, gm); const float f = __builtin_amdgcn_exp2f(mx - mn); l *= f; mx = mn;
; #pragma unroll
;         for (int d = 0; d < 2; ++d)
; #pragma unroll
;             for (int i = 0; i < 16; ++i) o[d][i] *= f; }
;     float l0 = 0.f, l1 = 0.f, l2 = 0.f, l3 = 0.f;
; #pragma unroll
;     for (int t = 0; t < NT; ++t)
; #pragma unroll
;         for (int i = 0; i < 16; i += 4) {
;             const float p0 = __builtin_amdgcn_exp2f(s[t][i] - mx), p1 = __builtin_amdgcn_exp2f(s[t][i + 1] - mx), p2 = __builtin_amdgcn_exp2f(s[t][i + 2] - mx), p3 = __builtin_amdgcn_exp2f(s[t][i + 3] - mx);
;             s[t][i] = p0; s[t][i + 1] = p1; s[t][i + 2] = p2; s[t][i + 3] = p3; l0 += p0; l1 += p1; l2 += p2; l3 += p3; }
	v_mfma_f32_32x32x16_bf16 v[32:47], v[124:127], v[120:123], v[32:47]
	v_add_u32_e32 v124, v147, v141
	s_waitcnt lgkmcnt(0)
	v_mfma_f32_32x32x16_bf16 v[48:63], v[186:189], v[120:123], v[48:63]
	ds_read_b128 v[120:123], v124
	ds_read_b128 v[124:127], v124 offset:4096
	s_waitcnt lgkmcnt(1)
	v_mfma_f32_32x32x16_bf16 v[32:47], v[120:123], v[116:119], v[32:47]
	v_add_u32_e32 v120, v147, v142
	s_waitcnt lgkmcnt(0)
	v_mfma_f32_32x32x16_bf16 v[48:63], v[124:127], v[116:119], v[48:63]
	ds_read_b128 v[116:119], v120
	ds_read_b128 v[120:123], v120 offset:4096
	s_waitcnt lgkmcnt(1)
	v_mfma_f32_32x32x16_bf16 v[32:47], v[116:119], v[112:115], v[32:47]
	s_waitcnt lgkmcnt(0)
	v_mfma_f32_32x32x16_bf16 v[48:63], v[120:123], v[112:115], v[48:63]
	s_nop 9
	v_cndmask_b32_e64 v32, v32, v227, s[40:41]
	v_cndmask_b32_e64 v36, v36, v227, s[94:95]
	v_cndmask_b32_e64 v33, v33, v227, s[0:1]
	v_cndmask_b32_e64 v112, v34, v227, s[38:39]
	v_cndmask_b32_e64 v37, v37, v227, s[92:93]
	v_cndmask_b32_e64 v113, v44, v227, s[54:55]
	v_max_f32_e32 v34, v36, v36
	v_max_f32_e32 v44, v32, v32
	v_cndmask_b32_e64 v35, v35, v227, s[96:97]
	v_cndmask_b32_e64 v39, v39, v227, s[88:89]
	v_max_f32_e32 v34, v44, v34
	v_max_f32_e32 v44, v37, v37
	v_max_f32_e32 v114, v33, v33
	v_max_f32_e32 v44, v114, v44
	v_max_f32_e32 v114, v39, v39
	v_max_f32_e32 v115, v35, v35
	v_cndmask_b32_e64 v38, v38, v227, s[90:91]
	v_cndmask_b32_e64 v42, v42, v227, s[58:59]
	v_cndmask_b32_e64 v43, v43, v227, s[56:57]
	v_cndmask_b32_e64 v47, v47, v227, s[76:77]
	v_max_f32_e32 v114, v115, v114
	v_cndmask_b32_e64 v40, v40, v227, s[62:63]
	v_cndmask_b32_e64 v41, v41, v227, s[60:61]
	v_cndmask_b32_e64 v45, v45, v227, s[52:53]
	v_cndmask_b32_e64 v46, v46, v227, s[50:51]
	v_max3_f32 v115, v112, v38, v42
	v_max3_f32 v114, v114, v43, v47
	v_max3_f32 v34, v34, v40, v113
	v_max3_f32 v44, v44, v41, v45
	v_max3_f32 v115, v115, v46, v50
	v_max3_f32 v114, v114, v51, v55
	v_max3_f32 v34, v34, v48, v52
	v_max3_f32 v44, v44, v49, v53
	v_max3_f32 v115, v115, v54, v58
	v_max3_f32 v114, v114, v59, v63
	v_max3_f32 v34, v34, v56, v60
	v_max3_f32 v44, v44, v57, v61
	v_max3_f32 v114, v115, v62, v114
	v_max3_f32 v34, v34, v44, v114
	v_mov_b32_e32 v44, v34
	s_nop 1
	v_permlane32_swap_b32_e32 v44, v34
	s_waitcnt lgkmcnt(0)
	v_max3_f32 v34, v163, v34, v44
	v_sub_f32_e32 v32, v32, v34
	v_exp_f32_e32 v114, v32
	v_sub_f32_e32 v32, v33, v34
	v_sub_f32_e32 v36, v36, v34
	v_exp_f32_e32 v33, v32
	v_sub_f32_e32 v32, v112, v34
	v_exp_f32_e32 v118, v36
	v_sub_f32_e32 v36, v37, v34
	v_exp_f32_e32 v112, v32
	v_sub_f32_e32 v32, v35, v34
	v_exp_f32_e32 v119, v36
	v_sub_f32_e32 v36, v38, v34
	v_exp_f32_e32 v35, v32
	v_exp_f32_e32 v120, v36
	v_sub_f32_e32 v36, v39, v34
	v_exp_f32_e32 v39, v36
	v_add_f32_e32 v115, 0, v33
	v_sub_f32_e32 v40, v40, v34
	v_add_f32_e32 v116, 0, v112
	v_add_f32_e32 v36, v119, v115
	v_exp_f32_e32 v115, v40
	v_sub_f32_e32 v40, v41, v34
	v_add_f32_e32 v117, 0, v35
	v_add_f32_e32 v37, v120, v116
	v_exp_f32_e32 v116, v40
	v_sub_f32_e32 v40, v42, v34
	v_add_f32_e32 v38, v39, v117
	v_exp_f32_e32 v117, v40
	v_sub_f32_e32 v40, v43, v34
	v_exp_f32_e32 v121, v40
	v_sub_f32_e32 v40, v113, v34
	v_exp_f32_e32 v113, v40
	v_sub_f32_e32 v40, v45, v34
	v_exp_f32_e32 v45, v40
	v_sub_f32_e32 v40, v46, v34
	v_exp_f32_e32 v46, v40
	v_sub_f32_e32 v40, v47, v34
	v_exp_f32_e32 v47, v40
	v_sub_f32_e32 v40, v48, v34
	v_exp_f32_e32 v48, v40
	v_sub_f32_e32 v40, v49, v34
	v_exp_f32_e32 v49, v40
	v_sub_f32_e32 v40, v50, v34
	v_exp_f32_e32 v50, v40
	v_sub_f32_e32 v40, v51, v34
	v_exp_f32_e32 v51, v40
	v_sub_f32_e32 v40, v52, v34
	v_exp_f32_e32 v52, v40
	v_sub_f32_e32 v40, v53, v34
	v_exp_f32_e32 v53, v40
	v_sub_f32_e32 v40, v54, v34
	v_exp_f32_e32 v54, v40
	v_sub_f32_e32 v40, v55, v34
	v_exp_f32_e32 v55, v40
	v_sub_f32_e32 v40, v56, v34
	v_exp_f32_e32 v56, v40
	v_sub_f32_e32 v40, v57, v34
	v_exp_f32_e32 v57, v40
	v_sub_f32_e32 v40, v58, v34
	v_exp_f32_e32 v58, v40
	v_sub_f32_e32 v40, v59, v34
	v_exp_f32_e32 v59, v40
	v_sub_f32_e32 v40, v60, v34
	v_add_f32_e32 v32, 0, v114
	v_exp_f32_e32 v60, v40
	v_sub_f32_e32 v40, v61, v34
	v_add_f32_e32 v32, v118, v32
	v_exp_f32_e32 v61, v40
	v_sub_f32_e32 v40, v62, v34
	v_add_f32_e32 v32, v115, v32
	v_add_f32_e32 v36, v116, v36
	v_add_f32_e32 v37, v117, v37
	v_add_f32_e32 v38, v121, v38
	v_exp_f32_e32 v62, v40
	v_sub_f32_e32 v40, v63, v34
	v_add_f32_e32 v32, v113, v32
	v_add_f32_e32 v36, v45, v36
	v_add_f32_e32 v37, v46, v37
	v_add_f32_e32 v38, v47, v38
	v_exp_f32_e32 v63, v40
	v_add_f32_e32 v32, v48, v32
	v_add_f32_e32 v36, v49, v36
	v_add_f32_e32 v37, v50, v37
	v_add_f32_e32 v38, v51, v38
	v_add_f32_e32 v32, v52, v32
	v_add_f32_e32 v36, v53, v36
	v_add_f32_e32 v37, v54, v37
	v_add_f32_e32 v38, v55, v38
	v_add_f32_e32 v32, v56, v32
	v_add_f32_e32 v36, v57, v36
	v_add_f32_e32 v37, v58, v37
	v_add_f32_e32 v38, v59, v38
	v_add_f32_e32 v32, v60, v32
	v_add_f32_e32 v36, v61, v36
	v_add_f32_e32 v37, v62, v37
	v_add_f32_e32 v38, v63, v38
	v_add_f32_e32 v32, v32, v36
	v_add_f32_e32 v36, v37, v38
	v_sub_f32_e32 v44, v163, v34
	v_add_f32_e32 v32, v32, v36
	v_cvt_pk_bf16_f32 v36, v114, v33
	v_add_u32_e32 v33, v148, v144
	v_exp_f32_e32 v44, v44
	ds_read_b64_tr_b16 v[40:41], v33 offset:49152
	ds_read_b64_tr_b16 v[42:43], v33 offset:50176
	v_cvt_pk_bf16_f32 v37, v112, v35
	v_cvt_pk_bf16_f32 v38, v118, v119
	v_cvt_pk_bf16_f32 v39, v120, v39
	v_pk_mul_f32 v[30:31], v[30:31], v[44:45] op_sel_hi:[1,0]
	v_pk_mul_f32 v[28:29], v[28:29], v[44:45] op_sel_hi:[1,0]
	v_pk_mul_f32 v[26:27], v[26:27], v[44:45] op_sel_hi:[1,0]
	v_pk_mul_f32 v[24:25], v[24:25], v[44:45] op_sel_hi:[1,0]
	v_pk_mul_f32 v[22:23], v[22:23], v[44:45] op_sel_hi:[1,0]
	v_pk_mul_f32 v[20:21], v[20:21], v[44:45] op_sel_hi:[1,0]
	v_pk_mul_f32 v[18:19], v[18:19], v[44:45] op_sel_hi:[1,0]
	v_pk_mul_f32 v[16:17], v[16:17], v[44:45] op_sel_hi:[1,0]
	v_add_u32_e32 v35, v148, v145
	v_pk_mul_f32 v[14:15], v[14:15], v[44:45] op_sel_hi:[1,0]
	s_waitcnt lgkmcnt(0)
; #define LAS __attribute__((address_space(3)))
; __device__ __forceinline__ s16x4 vtr(LAS const unsigned char* p) { return __builtin_bit_cast(s16x4, __builtin_amdgcn_ds_read_tr16_b64_v4i16((LAS v4i16_t*)p)); }
; template <int T0, int NT, bool FIRST>
; __device__ __forceinline__ void attn_group(LAS const unsigned char* Kl, LAS const unsigned char* Vl, const bf16x8 (&qf)[4], f32x16 (&o)[2], float& mx, float& l, int nb, int w, int lane) {
;     ...
; #pragma unroll
;     for (int t = 0; t < NT; ++t)
; #pragma unroll
;         for (int s2 = 0; s2 < 2; ++s2) {
;             u32x4 pw; pw.x = cvt_pk_bf16(s[t][8 * s2 + 0], s[t][8 * s2 + 1]); pw.y = cvt_pk_bf16(s[t][8 * s2 + 2], s[t][8 * s2 + 3]);
;             pw.z = cvt_pk_bf16(s[t][8 * s2 + 4], s[t][8 * s2 + 5]); pw.w = cvt_pk_bf16(s[t][8 * s2 + 6], s[t][8 * s2 + 7]);
;             const bf16x8 pf = __builtin_bit_cast(bf16x8, pw);
; #pragma unroll
;             for (int d = 0; d < 2; ++d) {
;                 LAS const unsigned char* vp = vb + (t * 32 + s2 * 16) * 128 + ((d * 64) ^ vsw);
;                 const s16x4 lo = vtr(vp), hi4 = vtr(vp + 8 * 128);
;                 const bf16x8 vf = (bf16x8){lo[0], lo[1], lo[2], lo[3], hi4[0], hi4[1], hi4[2], hi4[3]};
;                 o[d] = __builtin_amdgcn_mfma_f32_32x32x16_bf16(vf, pf, o[d], 0, 0, 0);
;             }
;         }
; }
; template <bool FINAL>
; __device__ __forceinline__ void attn_compute(LAS unsigned char* lds, const bf16_t* proj, const AttnItem& t, const AttnItem& nxt, bool more, bf16x8 (&qf)[4], bf16_t* o23, float* lse23, bf16_t* ycat, int lane, int wid) {
;     ...
;     l += __shfl_xor(l, 32);
;     attn_load_q(proj, nxt, qf, lane, wid);
;     const float lse = mx + __builtin_amdgcn_logf(l);
;     if (!FINAL) {
;         const float c1 = 1.0f / l;
;         if (hi == 0) lse23[(size_t)t.br * M * NH + hrow] = lse;
	v_mfma_f32_32x32x16_bf16 v[16:31], v[40:43], v[36:39], v[16:31]
	ds_read_b64_tr_b16 v[40:41], v35 offset:49152
	ds_read_b64_tr_b16 v[42:43], v35 offset:50176
	v_mul_f32_e64 v12, v12, v44
	v_mul_f32_e64 v13, v13, v44
	v_mul_f32_e64 v10, v10, v44
	v_mul_f32_e64 v11, v11, v44
	v_pk_mul_f32 v[8:9], v[8:9], v[44:45] op_sel_hi:[1,0]
	v_pk_mul_f32 v[6:7], v[6:7], v[44:45] op_sel_hi:[1,0]
	v_pk_mul_f32 v[4:5], v[4:5], v[44:45] op_sel_hi:[1,0]
	v_pk_mul_f32 v[2:3], v[2:3], v[44:45] op_sel_hi:[1,0]
	v_pk_mul_f32 v[0:1], v[0:1], v[44:45] op_sel_hi:[1,0]
	v_fmac_f32_e32 v32, v164, v44
	s_waitcnt lgkmcnt(0)
	v_mfma_f32_32x32x16_bf16 v[0:15], v[40:43], v[36:39], v[0:15]
	ds_read_b64_tr_b16 v[40:41], v33 offset:51200
	ds_read_b64_tr_b16 v[42:43], v33 offset:52224
	ds_read_b64_tr_b16 v[198:199], v35 offset:51200
	ds_read_b64_tr_b16 v[200:201], v35 offset:52224
	v_cvt_pk_bf16_f32 v36, v115, v116
	v_cvt_pk_bf16_f32 v37, v117, v121
	v_cvt_pk_bf16_f32 v38, v113, v45
	v_cvt_pk_bf16_f32 v39, v46, v47
	s_waitcnt lgkmcnt(2)
	s_nop 0
	v_mfma_f32_32x32x16_bf16 v[16:31], v[40:43], v[36:39], v[16:31]
	s_waitcnt lgkmcnt(0)
	v_mfma_f32_32x32x16_bf16 v[0:15], v[198:201], v[36:39], v[0:15]
	ds_read_b64_tr_b16 v[40:41], v33 offset:53248
	ds_read_b64_tr_b16 v[42:43], v33 offset:54272
	ds_read_b64_tr_b16 v[198:199], v35 offset:53248
	ds_read_b64_tr_b16 v[200:201], v35 offset:54272
	v_cvt_pk_bf16_f32 v36, v48, v49
	v_cvt_pk_bf16_f32 v37, v50, v51
	v_cvt_pk_bf16_f32 v38, v52, v53
	v_cvt_pk_bf16_f32 v39, v54, v55
	s_waitcnt lgkmcnt(2)
	s_nop 0
	v_mfma_f32_32x32x16_bf16 v[16:31], v[40:43], v[36:39], v[16:31]
	s_waitcnt lgkmcnt(0)
	v_mfma_f32_32x32x16_bf16 v[0:15], v[198:201], v[36:39], v[0:15]
	ds_read_b64_tr_b16 v[40:41], v33 offset:55296
	ds_read_b64_tr_b16 v[42:43], v33 offset:56320
	v_cvt_pk_bf16_f32 v36, v56, v57
	v_cvt_pk_bf16_f32 v37, v58, v59
	v_cvt_pk_bf16_f32 v38, v60, v61
	v_cvt_pk_bf16_f32 v39, v62, v63
	ds_bpermute_b32 v33, v150, v32
	s_waitcnt lgkmcnt(1)
	v_mfma_f32_32x32x16_bf16 v[16:31], v[40:43], v[36:39], v[16:31]
	ds_read_b64_tr_b16 v[40:41], v35 offset:55296
	ds_read_b64_tr_b16 v[42:43], v35 offset:56320
	v_or_b32_e32 v35, s49, v149
	v_lshlrev_b32_e32 v35, s3, v35
	v_add_u32_e32 v35, s98, v35
	s_addc_u32 s3, s7, 0
	s_waitcnt lgkmcnt(0)
	v_mfma_f32_32x32x16_bf16 v[0:15], v[40:43], v[36:39], v[0:15]
	v_lshlrev_b32_e32 v37, 7, v35
	v_and_b32_e32 v36, 0x3f800, v35
	v_and_b32_e32 v37, 0x780, v37
	v_bfe_u32 v35, v35, 4, 7
	v_or3_b32 v35, v37, v36, v35
	v_lshlrev_b32_e32 v168, 7, v35
	v_lshl_add_u64 v[36:37], s[2:3], 0, v[168:169]
	v_lshl_add_u64 v[36:37], v[128:129], 1, v[36:37]
	global_load_dwordx4 v[124:127], v[36:37], off
	global_load_dwordx4 v[120:123], v[36:37], off offset:32
	global_load_dwordx4 v[116:119], v[36:37], off offset:64
	global_load_dwordx4 v[112:115], v[36:37], off offset:96
	s_and_saveexec_b64 s[2:3], s[4:5]
	s_xor_b64 s[2:3], exec, s[2:3]
	s_ashr_i32 s49, s48, 31
	s_or_saveexec_b64 s[2:3], s[2:3]
	v_lshl_or_b32 v35, s25, 7, v146
	v_mov_b32_e32 v36, s24
	v_mad_i32_i24 v35, s20, v35, v36
	v_lshlrev_b32_e32 v37, 7, v35
	v_and_b32_e32 v36, 0xfffff800, v35
	v_and_b32_e32 v37, 0x780, v37
	v_bfe_u32 v35, v35, 4, 7
	s_lshl_b32 s6, s23, 16
	s_lshl_b32 s7, s22, 13
	v_or3_b32 v35, v37, v36, v35
	s_or_b32 s6, s6, s7
	v_add_u32_e32 v168, s6, v35
	v_add_f32_e32 v35, v32, v33
	v_mov_b64_e32 v[32:33], s[48:49]
	s_xor_b64 exec, exec, s[2:3]
	s_cbranch_execz .LBB0_107
	v_log_f32_e32 v32, v35
	s_ashr_i32 s49, s48, 31
	s_lshl_b64 s[6:7], s[48:49], 20
	v_readlane_b32 s22, v251, 61
	v_readlane_b32 s23, v251, 62
	s_add_u32 s6, s22, s6
	s_addc_u32 s7, s23, s7
	v_add_f32_e32 v34, v34, v32
	v_lshl_add_u64 v[32:33], v[168:169], 2, s[6:7]
	global_store_dword v[32:33], v34, off
	v_mov_b64_e32 v[32:33], s[48:49]
	s_branch .LBB0_107

; #define LAS __attribute__((address_space(3)))
; __device__ __forceinline__ int tpos(int t) { return (t & ~2047) | ((t & 15) << 7) | ((t & 2047) >> 4); }
; template <int T0, int NT, bool FIRST>
; __device__ __forceinline__ void attn_group(LAS const unsigned char* Kl, LAS const unsigned char* Vl, const bf16x8 (&qf)[4], f32x16 (&o)[2], float& mx, float& l, int nb, int w, int lane) {
;     ...
;     f32x16 s[NT];
; #pragma unroll
;     for (int t = 0; t < NT; ++t) { const float z = (T0 + t < 4 && nb == 0 && w + T0 + t < 4) ? NEGBIG : 0.f;
;         s[t] = (f32x16){z, z, z, z, z, z, z, z, z, z, z, z, z, z, z, z}; }
;     {
;         LAS const unsigned char* kp = Kl + (32 * (w + T0) + r32) * 128;
;         const int sw = (r32 >> 1) & 7;
; #pragma unroll
;         for (int ks = 0; ks < 4; ++ks) {
;             bf16x8 kf[NT];
; #pragma unroll
;             for (int t = 0; t < NT; ++t) kf[t] = *(LAS const bf16x8*)(kp + t * 4096 + (((2 * ks + hi) ^ sw) * 16));
; #pragma unroll
;             for (int t = 0; t < NT; ++t) s[t] = __builtin_amdgcn_mfma_f32_32x32x16_bf16(kf[t], qf[ks], s[t], 0, 0, 0);
; template <bool FINAL>
; __device__ __forceinline__ void attn_compute(LAS unsigned char* lds, const bf16_t* proj, const AttnItem& t, const AttnItem& nxt, bool more, bf16x8 (&qf)[4], bf16_t* o23, float* lse23, bf16_t* ycat, int lane, int wid) {
;     ...
;     const int tok = (nb * 128 + 32 * w + r32) * t.dil + t.r;
;     const size_t qrow = (size_t)t.b * SEQ + tok, hrow = (size_t)(t.b * NH + t.h) * SEQ + tpos(tok);
;     float l2 = 0.f, l3 = 0.f; u32x2 a2[8], a3[8];
;     if (FINAL) { l2 = lse23[hrow]; l3 = lse23[(size_t)M * NH + hrow];
;         const bf16_t* o2 = o23 + hrow * HD + 4 * hi; const bf16_t* o3 = o2 + (size_t)M * AW;
; #pragma unroll
;         for (int i = 0; i < 8; ++i) { a2[i] = *(const u32x2*)(o2 + 32 * (i >> 2) + 8 * (i & 3)); a3[i] = *(const u32x2*)(o3 + 32 * (i >> 2) + 8 * (i & 3)); } }
.LBB0_474:
	s_lshl_b32 s10, s14, 1
	s_add_i32 s10, s10, s16
	s_ashr_i32 s20, s10, 9
	s_bfe_u32 s21, s10, 0x30006
	s_lshl_b32 s14, s20, 3
	s_and_b32 s22, s10, 63
	s_or_b32 s24, s14, s21
	s_lshl_b32 s14, s22, 7
	s_and_b32 s10, s14, 0x1f00
	s_add_i32 s19, s10, 0xffffff80
	v_add_u32_e32 v0, s19, v138
	v_add_u32_e32 v1, s10, v138
	v_cmp_gt_i32_e32 vcc, 0, v0
	s_ashr_i32 s25, s24, 31
	s_lshl_b64 s[26:27], s[24:25], 21
	v_cndmask_b32_e32 v187, v0, v1, vcc
	v_add_u32_e32 v0, s19, v139
	v_add_u32_e32 v1, s10, v139
	v_cmp_gt_i32_e32 vcc, 0, v0
	v_add_u32_e32 v33, v147, v148
	v_lshl_add_u64 v[88:89], v[98:99], 0, s[26:27]
	v_cndmask_b32_e32 v87, v0, v1, vcc
	v_add_u32_e32 v0, s19, v140
	v_add_u32_e32 v1, s10, v140
	v_cmp_gt_i32_e32 vcc, 0, v0
	ds_read_b128 v[10:13], v33
	ds_read_b128 v[34:37], v33 offset:4096
	v_cndmask_b32_e32 v86, v0, v1, vcc
	v_add_u32_e32 v0, s19, v141
	v_add_u32_e32 v1, s10, v141
	v_cmp_gt_i32_e32 vcc, 0, v0
	s_ashr_i32 s99, s98, 31
	v_readlane_b32 s44, v250, 4
	v_cndmask_b32_e32 v85, v0, v1, vcc
	v_add_u32_e32 v0, s19, v142
	v_add_u32_e32 v1, s10, v142
	v_cmp_gt_i32_e32 vcc, 0, v0
	v_readlane_b32 s45, v250, 5
	v_add_u32_e32 v131, v155, v149
	v_cndmask_b32_e32 v84, v0, v1, vcc
	v_add_u32_e32 v1, s10, v143
	s_lshl_b32 s10, s98, 3
	s_or_b32 s26, s10, s12
	v_add_u32_e32 v0, s19, v143
	s_ashr_i32 s27, s26, 31
	s_lshl_b32 s19, s23, 7
	s_lshl_b64 s[26:27], s[26:27], 13
	s_and_b32 s10, s19, 0x1800
	v_cmp_gt_i32_e32 vcc, 0, v0
	s_cmp_eq_u32 s23, 0
	v_or_b32_e32 v188, s19, v146
	v_cndmask_b32_e32 v186, v0, v1, vcc
	s_cselect_b64 vcc, -1, 0
	v_bfe_u32 v1, v188, 4, 7
	v_cndmask_b32_e32 v32, 0, v227, vcc
	s_and_b64 vcc, vcc, s[44:45]
	s_or_b32 s23, s23, s18
	v_or_b32_e32 v1, s10, v1
	s_cmp_eq_u32 s23, 0
	v_or3_b32 v2, v1, v145, s26
	v_mov_b32_e32 v3, s27
	v_readlane_b32 s26, v251, 61
	v_cndmask_b32_e32 v16, 0, v227, vcc
	s_cselect_b64 vcc, -1, 0
	v_readlane_b32 s27, v251, 62
	v_or_b32_e32 v1, s14, v144
	v_cndmask_b32_e32 v0, 0, v227, vcc
	v_lshl_add_u64 v[82:83], v[2:3], 2, s[26:27]
	v_lshlrev_b64 v[2:3], 7, v[2:3]
	v_lshrrev_b32_e32 v1, 4, v1
	v_mov_b32_e32 v17, v16
	v_mov_b32_e32 v18, v16
	v_mov_b32_e32 v19, v16
	v_mov_b32_e32 v20, v16
	v_mov_b32_e32 v21, v16
	v_mov_b32_e32 v22, v16
	v_mov_b32_e32 v23, v16
	v_mov_b32_e32 v24, v16
	v_mov_b32_e32 v25, v16
	v_mov_b32_e32 v26, v16
	v_mov_b32_e32 v27, v16
	v_mov_b32_e32 v28, v16
	v_mov_b32_e32 v29, v16
	v_mov_b32_e32 v30, v16
	v_mov_b32_e32 v31, v16
	v_lshl_add_u64 v[106:107], v[100:101], 0, v[2:3]
	v_or_b32_e32 v90, s14, v1
	v_mov_b32_e32 v1, v0
	v_mov_b32_e32 v2, v0
	v_mov_b32_e32 v3, v0
	v_mov_b32_e32 v4, v0
	v_mov_b32_e32 v5, v0
	v_mov_b32_e32 v6, v0
	v_mov_b32_e32 v7, v0
	v_mov_b32_e32 v8, v0
	s_waitcnt vmcnt(3) lgkmcnt(1)
	v_mfma_f32_32x32x16_bf16 v[16:31], v[10:13], v[76:79], v[16:31]
	v_mov_b32_e32 v9, v0
	v_mov_b32_e32 v10, v0
	v_mov_b32_e32 v11, v0
	v_mov_b32_e32 v12, v0
	v_mov_b32_e32 v13, v0
	v_mov_b32_e32 v14, v0
	v_mov_b32_e32 v15, v0
	s_mov_b32 s10, 0x100000
	v_add_co_u32_e32 v80, vcc, s10, v82
	s_waitcnt lgkmcnt(0)
	v_mfma_f32_32x32x16_bf16 v[0:15], v[34:37], v[76:79], v[0:15]
	ds_read_b128 v[34:37], v33 offset:8192
	v_add_u32_e32 v33, v147, v149
	ds_read_b128 v[50:53], v33
	v_addc_co_u32_e32 v81, vcc, 0, v83, vcc
	s_brev_b32 s10, 64
	v_add_co_u32_e32 v104, vcc, s10, v106
	s_waitcnt vmcnt(2) lgkmcnt(0)
	v_mfma_f32_32x32x16_bf16 v[16:31], v[50:53], v[72:75], v[16:31]
	ds_read_b128 v[50:53], v33 offset:4096
	v_addc_co_u32_e32 v105, vcc, 0, v107, vcc
	s_lshl_b64 s[24:25], s[24:25], 20
	v_readlane_b32 s26, v251, 59
	v_readlane_b32 s27, v251, 60
	s_add_u32 vcc_lo, s26, s24
	s_waitcnt lgkmcnt(0)
	v_mfma_f32_32x32x16_bf16 v[0:15], v[50:53], v[72:75], v[0:15]
	ds_read_b128 v[50:53], v33 offset:8192
	v_add_u32_e32 v33, v147, v150
	s_addc_u32 vcc_hi, s27, s25
	v_readlane_b32 s24, v250, 6
	v_readlane_b32 s25, v250, 7
	s_movk_i32 s10, 0x187f
	v_readlane_b32 s26, v251, 57
	v_mfma_f32_32x32x16_bf16 v[34:49], v[34:37], v[76:79], 0
	v_readlane_b32 s27, v251, 58
	s_mov_b32 s23, s22
	s_waitcnt lgkmcnt(0)
	v_mfma_f32_32x32x16_bf16 v[34:49], v[50:53], v[72:75], v[34:49]
	ds_read_b128 v[50:53], v33
	s_waitcnt vmcnt(1) lgkmcnt(0)
	v_mfma_f32_32x32x16_bf16 v[16:31], v[50:53], v[68:71], v[16:31]
	ds_read_b128 v[50:53], v33 offset:4096
	s_waitcnt lgkmcnt(0)
	v_mfma_f32_32x32x16_bf16 v[0:15], v[50:53], v[68:71], v[0:15]
	ds_read_b128 v[50:53], v33 offset:8192
	v_add_u32_e32 v33, v147, v151
	s_waitcnt lgkmcnt(0)
	v_mfma_f32_32x32x16_bf16 v[34:49], v[50:53], v[68:71], v[34:49]
	ds_read_b128 v[50:53], v33
	s_waitcnt vmcnt(0) lgkmcnt(0)
	v_mfma_f32_32x32x16_bf16 v[16:31], v[50:53], v[64:67], v[16:31]
	global_load_dwordx2 v[218:219], v[104:105], off
	global_load_dwordx2 v[220:221], v[106:107], off
	global_load_dwordx2 v[230:231], v[106:107], off offset:16
	global_load_dwordx2 v[232:233], v[104:105], off offset:16
	global_load_dwordx2 v[234:235], v[106:107], off offset:32
	global_load_dwordx2 v[236:237], v[104:105], off offset:32
	global_load_dwordx2 v[238:239], v[106:107], off offset:48
	global_load_dwordx2 v[240:241], v[104:105], off offset:48
	global_load_dwordx2 v[242:243], v[106:107], off offset:64
	global_load_dwordx2 v[244:245], v[104:105], off offset:64
	global_load_dwordx2 v[246:247], v[106:107], off offset:80
	global_load_dwordx2 v[248:249], v[104:105], off offset:80
	global_load_dwordx2 v[254:255], v[106:107], off offset:96
	ds_read_b128 v[50:53], v33 offset:4096
	s_waitcnt lgkmcnt(0)
	v_mfma_f32_32x32x16_bf16 v[0:15], v[50:53], v[64:67], v[0:15]
	ds_read_b128 v[50:53], v33 offset:8192
	s_waitcnt lgkmcnt(0)
; __device__ __forceinline__ int crow(int i, int hi) { return (i & 3) + 8 * (i >> 2) + 4 * hi; }
; template <int T0, int NT, bool FIRST>
; __device__ __forceinline__ void attn_group(LAS const unsigned char* Kl, LAS const unsigned char* Vl, const bf16x8 (&qf)[4], f32x16 (&o)[2], float& mx, float& l, int nb, int w, int lane) {
;     ...
; #pragma unroll
;     for (int t = 0; t < NT; ++t) {
;         const int tt = T0 + t;
;         if (tt == 0) {
; #pragma unroll
;             for (int i = 0; i < 16; ++i) if (crow(i, hi) < r32) s[t][i] = NEGBIG; }
;         if (tt == 4) {
; #pragma unroll
;             for (int i = 0; i < 16; ++i) if (crow(i, hi) > r32) s[t][i] = NEGBIG; }
;     }
;     float m0 = s[0][0], m1 = s[0][1], m2 = s[0][2], m3 = s[0][3];
; #pragma unroll
;     for (int t = 0; t < NT; ++t)
; #pragma unroll
;         for (int i = 0; i < 16; i += 4) { m0 = fmaxf(m0, s[t][i]); m1 = fmaxf(m1, s[t][i + 1]); m2 = fmaxf(m2, s[t][i + 2]); m3 = fmaxf(m3, s[t][i + 3]); }
;     float gm = fmaxf(fmaxf(m0, m1), fmaxf(m2, m3));
;     gm = fmaxf(gm, __shfl_xor(gm, 32));
;     if (FIRST) mx = gm;
;     else { const float mn = fmaxf(mx, gm); const float f = __builtin_amdgcn_exp2f(mx - mn); l *= f; mx = mn;
; #pragma unroll
;         for (int d = 0; d < 2; ++d)
; #pragma unroll
;             for (int i = 0; i < 16; ++i) o[d][i] *= f; }
;     float l0 = 0.f, l1 = 0.f, l2 = 0.f, l3 = 0.f;
; #pragma unroll
;     for (int t = 0; t < NT; ++t)
; #pragma unroll
;         for (int i = 0; i < 16; i += 4) {
;             const float p0 = __builtin_amdgcn_exp2f(s[t][i] - mx), p1 = __builtin_amdgcn_exp2f(s[t][i + 1] - mx), p2 = __builtin_amdgcn_exp2f(s[t][i + 2] - mx), p3 = __builtin_amdgcn_exp2f(s[t][i + 3] - mx);
;             s[t][i] = p0; s[t][i + 1] = p1; s[t][i + 2] = p2; s[t][i + 3] = p3; l0 += p0; l1 += p1; l2 += p2; l3 += p3; }
	v_mfma_f32_32x32x16_bf16 v[34:49], v[50:53], v[64:67], v[34:49]
	s_nop 11
	v_cndmask_b32_e64 v33, v34, v227, s[24:25]
	v_cndmask_b32_e64 v91, v33, v34, s[4:5]
	v_readlane_b32 s24, v250, 8
	v_max_f32_e32 v33, v20, v20
	v_max_f32_e32 v34, v16, v16
	v_readlane_b32 s25, v250, 9
	v_max_f32_e32 v33, v34, v33
	v_max3_f32 v33, v33, v24, v28
	v_cndmask_b32_e64 v113, v36, v227, s[24:25]
	v_readlane_b32 s24, v250, 10
	v_readlane_b32 s25, v250, 11
	v_max3_f32 v33, v33, v0, v4
	v_cndmask_b32_e64 v112, v227, v35, s[4:5]
	v_cndmask_b32_e64 v114, v37, v227, s[24:25]
	v_readlane_b32 s24, v250, 12
	v_max_f32_e32 v34, v21, v21
	v_max_f32_e32 v35, v17, v17
	v_max3_f32 v122, v33, v8, v12
	v_add_u32_e32 v33, v155, v148
	v_readlane_b32 s25, v250, 13
	v_max_f32_e32 v34, v35, v34
	v_max_f32_e32 v35, v23, v23
	v_max_f32_e32 v36, v19, v19
	ds_read_b128 v[50:53], v33
	ds_read_b128 v[92:95], v33 offset:4096
	v_cndmask_b32_e64 v115, v38, v227, s[24:25]
	v_readlane_b32 s24, v250, 14
	v_max_f32_e32 v35, v36, v35
	v_max3_f32 v36, v18, v22, v26
	v_max3_f32 v34, v34, v25, v29
	v_readlane_b32 s25, v250, 15
	v_max3_f32 v35, v35, v27, v31
	v_max3_f32 v36, v36, v30, v2
	v_max3_f32 v34, v34, v1, v5
	v_cndmask_b32_e64 v117, v39, v227, s[24:25]
	v_cndmask_b32_e64 v118, v40, v227, s[46:47]
	v_cndmask_b32_e64 v119, v41, v227, s[48:49]
	v_cndmask_b32_e64 v121, v42, v227, s[50:51]
	v_cndmask_b32_e64 v123, v43, v227, s[52:53]
	v_cndmask_b32_e64 v124, v44, v227, s[54:55]
	v_cndmask_b32_e64 v125, v45, v227, s[56:57]
	v_cndmask_b32_e64 v126, v46, v227, s[58:59]
	v_cndmask_b32_e64 v127, v47, v227, s[60:61]
	v_cndmask_b32_e64 v128, v48, v227, s[62:63]
	v_max3_f32 v116, v35, v3, v7
	v_max3_f32 v120, v36, v6, v10
	v_max3_f32 v130, v34, v9, v13
	v_cndmask_b32_e64 v48, 0, v32, s[66:67]
	v_mov_b32_e32 v33, v32
	v_mov_b32_e32 v34, v32
	v_mov_b32_e32 v35, v32
	v_mov_b32_e32 v36, v32
	v_mov_b32_e32 v37, v32
	v_mov_b32_e32 v38, v32
	v_mov_b32_e32 v39, v32
	v_mov_b32_e32 v40, v32
	v_mov_b32_e32 v41, v32
	v_mov_b32_e32 v42, v32
	v_mov_b32_e32 v43, v32
	v_mov_b32_e32 v44, v32
	v_mov_b32_e32 v45, v32
	v_mov_b32_e32 v46, v32
	v_mov_b32_e32 v47, v32
	v_cndmask_b32_e64 v129, v49, v227, s[64:65]
	v_mov_b32_e32 v49, v48
	s_waitcnt lgkmcnt(1)
	v_mfma_f32_32x32x16_bf16 v[32:47], v[50:53], v[76:79], v[32:47]
	v_mov_b32_e32 v50, v48
	v_mov_b32_e32 v51, v48
	v_mov_b32_e32 v52, v48
	v_mov_b32_e32 v53, v48
	v_mov_b32_e32 v54, v48
	v_mov_b32_e32 v55, v48
	v_mov_b32_e32 v56, v48
	v_mov_b32_e32 v57, v48
	v_mov_b32_e32 v58, v48
	v_mov_b32_e32 v59, v48
	v_mov_b32_e32 v60, v48
	v_mov_b32_e32 v61, v48
	v_mov_b32_e32 v62, v48
	v_mov_b32_e32 v63, v48
	ds_read_b128 v[108:111], v131
	global_load_dword v80, v[80:81], off
	s_waitcnt lgkmcnt(1)
	v_mfma_f32_32x32x16_bf16 v[48:63], v[92:95], v[76:79], v[48:63]
	v_max3_f32 v76, v116, v11, v15
	v_max3_f32 v77, v120, v14, v113
	v_max3_f32 v94, v76, v114, v119
	v_max3_f32 v95, v77, v118, v124
	ds_read_b128 v[76:79], v131 offset:4096
	v_max3_f32 v92, v122, v91, v115
	v_max3_f32 v93, v130, v112, v117
	v_max3_f32 v94, v94, v125, v129
	s_waitcnt lgkmcnt(1)
	v_mfma_f32_32x32x16_bf16 v[32:47], v[108:111], v[72:75], v[32:47]
	v_max3_f32 v92, v92, v121, v126
	v_max3_f32 v93, v93, v123, v127
	v_max3_f32 v94, v95, v128, v94
	v_add_u32_e32 v109, v155, v150
	v_max3_f32 v108, v92, v93, v94
	ds_read_b128 v[92:95], v109
	s_waitcnt lgkmcnt(1)
	v_mfma_f32_32x32x16_bf16 v[48:63], v[76:79], v[72:75], v[48:63]
	v_mov_b32_e32 v72, v108
	s_nop 1
	v_permlane32_swap_b32_e32 v72, v108
	s_waitcnt lgkmcnt(0)
	v_max_f32_e32 v76, v72, v72
	ds_read_b128 v[72:75], v109 offset:4096
	v_mfma_f32_32x32x16_bf16 v[32:47], v[92:95], v[68:71], v[32:47]
	v_max_f32_e32 v109, v108, v76
	v_add_u32_e32 v92, v155, v151
	v_sub_f32_e32 v19, v19, v109
	ds_read_b128 v[76:79], v92
	v_exp_f32_e32 v19, v19
	v_sub_f32_e32 v23, v23, v109
	v_exp_f32_e32 v23, v23
	s_waitcnt lgkmcnt(1)
	v_mfma_f32_32x32x16_bf16 v[48:63], v[72:75], v[68:71], v[48:63]
	v_add_f32_e32 v68, 0, v19
	v_sub_f32_e32 v27, v27, v109
	v_add_f32_e32 v72, v23, v68
	ds_read_b128 v[68:71], v92 offset:4096
	v_exp_f32_e32 v192, v27
	v_sub_f32_e32 v27, v31, v109
	v_exp_f32_e32 v193, v27
	s_waitcnt lgkmcnt(1)
	v_mfma_f32_32x32x16_bf16 v[32:47], v[76:79], v[64:67], v[32:47]
	v_sub_f32_e32 v3, v3, v109
	v_exp_f32_e32 v194, v3
	v_sub_f32_e32 v3, v7, v109
	v_sub_f32_e32 v20, v20, v109
	v_sub_f32_e32 v24, v24, v109
	v_exp_f32_e32 v20, v20
	v_exp_f32_e32 v81, v24
	s_waitcnt lgkmcnt(0)
	v_mfma_f32_32x32x16_bf16 v[48:63], v[68:71], v[64:67], v[48:63]
	s_nop 2
	v_cndmask_b32_e64 v27, v32, v227, s[4:5]
	v_cndmask_b32_e64 v36, v36, v227, s[90:91]
	v_cndmask_b32_e64 v31, v33, v227, s[96:97]
	v_cndmask_b32_e64 v37, v37, v227, s[88:89]
	v_max_f32_e32 v32, v36, v36
	v_max_f32_e32 v33, v27, v27
	v_cndmask_b32_e64 v35, v35, v227, s[92:93]
	v_cndmask_b32_e64 v39, v39, v227, s[6:7]
	v_max_f32_e32 v32, v33, v32
	v_max_f32_e32 v33, v37, v37
	v_max_f32_e32 v64, v31, v31
	v_max_f32_e32 v33, v64, v33
	v_max_f32_e32 v64, v39, v39
	v_max_f32_e32 v65, v35, v35
	v_cndmask_b32_e64 v34, v34, v227, s[94:95]
	v_cndmask_b32_e64 v38, v38, v227, s[42:43]
	v_cndmask_b32_e64 v42, v42, v227, s[0:1]
	v_cndmask_b32_e64 v43, v43, v227, s[2:3]
	v_cndmask_b32_e64 v47, v47, v227, s[68:69]
	v_max_f32_e32 v64, v65, v64
	v_cndmask_b32_e64 v40, v40, v227, s[40:41]
	v_cndmask_b32_e64 v41, v41, v227, s[38:39]
	v_cndmask_b32_e64 v44, v44, v227, s[28:29]
	v_cndmask_b32_e64 v45, v45, v227, s[76:77]
	v_cndmask_b32_e64 v46, v46, v227, s[70:71]
	v_max3_f32 v65, v34, v38, v42
	v_max3_f32 v64, v64, v43, v47
	v_max3_f32 v32, v32, v40, v44
	v_max3_f32 v33, v33, v41, v45
	v_max3_f32 v65, v65, v46, v50
	v_max3_f32 v64, v64, v51, v55
	v_max3_f32 v32, v32, v48, v52
	v_max3_f32 v33, v33, v49, v53
	v_max3_f32 v65, v65, v54, v58
	v_max3_f32 v64, v64, v59, v63
	v_max3_f32 v32, v32, v56, v60
	v_max3_f32 v33, v33, v57, v61
	v_max3_f32 v64, v65, v62, v64
	v_max3_f32 v32, v32, v33, v64
	ds_bpermute_b32 v33, v157, v32
	v_exp_f32_e32 v66, v3
	v_sub_f32_e32 v24, v25, v109
	v_sub_f32_e32 v0, v0, v109
	v_exp_f32_e32 v198, v0
	s_waitcnt lgkmcnt(0)
; template <int T0, int NT, bool FIRST>
; __device__ __forceinline__ void attn_group(LAS const unsigned char* Kl, LAS const unsigned char* Vl, const bf16x8 (&qf)[4], f32x16 (&o)[2], float& mx, float& l, int nb, int w, int lane) {
;     ...
;     float m0 = s[0][0], m1 = s[0][1], m2 = s[0][2], m3 = s[0][3];
; #pragma unroll
;     for (int t = 0; t < NT; ++t)
; #pragma unroll
;         for (int i = 0; i < 16; i += 4) { m0 = fmaxf(m0, s[t][i]); m1 = fmaxf(m1, s[t][i + 1]); m2 = fmaxf(m2, s[t][i + 2]); m3 = fmaxf(m3, s[t][i + 3]); }
;     float gm = fmaxf(fmaxf(m0, m1), fmaxf(m2, m3));
;     gm = fmaxf(gm, __shfl_xor(gm, 32));
;     if (FIRST) mx = gm;
;     else { const float mn = fmaxf(mx, gm); const float f = __builtin_amdgcn_exp2f(mx - mn); l *= f; mx = mn;
; #pragma unroll
;         for (int d = 0; d < 2; ++d)
; #pragma unroll
;             for (int i = 0; i < 16; ++i) o[d][i] *= f; }
;     float l0 = 0.f, l1 = 0.f, l2 = 0.f, l3 = 0.f;
; #pragma unroll
;     for (int t = 0; t < NT; ++t)
; #pragma unroll
;         for (int i = 0; i < 16; i += 4) {
;             const float p0 = __builtin_amdgcn_exp2f(s[t][i] - mx), p1 = __builtin_amdgcn_exp2f(s[t][i + 1] - mx), p2 = __builtin_amdgcn_exp2f(s[t][i + 2] - mx), p3 = __builtin_amdgcn_exp2f(s[t][i + 3] - mx);
;             s[t][i] = p0; s[t][i + 1] = p1; s[t][i + 2] = p2; s[t][i + 3] = p3; l0 += p0; l1 += p1; l2 += p2; l3 += p3; }
;     l += (l0 + l1) + (l2 + l3);
	v_max3_f32 v7, v109, v32, v33
	v_sub_f32_e32 v3, v27, v7
	v_exp_f32_e32 v67, v3
	v_add_f32_e32 v3, v192, v72
	v_add_f32_e32 v3, v193, v3
	v_add_f32_e32 v168, v194, v3
	v_and_or_b32 v3, v90, s10, v145
	v_pk_add_f32 v[32:33], v[66:67], v[168:169]
	v_lshlrev_b32_e32 v168, 7, v3
	v_sub_f32_e32 v3, v16, v109
	v_exp_f32_e32 v16, v3
	global_load_dword v27, v[82:83], off
	v_sub_f32_e32 v3, v17, v109
	v_exp_f32_e32 v82, v24
	v_sub_f32_e32 v24, v26, v109
	v_sub_f32_e32 v26, v28, v109
	v_exp_f32_e32 v17, v3
	v_sub_f32_e32 v3, v18, v109
	v_exp_f32_e32 v195, v26
	v_exp_f32_e32 v18, v3
	v_add_f32_e32 v3, 0, v16
	v_add_f32_e32 v3, v20, v3
	v_add_f32_e32 v3, v81, v3
	v_sub_f32_e32 v0, v1, v109
	v_add_f32_e32 v3, v195, v3
	v_exp_f32_e32 v199, v0
	v_sub_f32_e32 v0, v2, v109
	v_exp_f32_e32 v200, v0
	v_add_f32_e32 v0, v198, v3
	v_sub_f32_e32 v3, v5, v109
	v_exp_f32_e32 v201, v3
	v_sub_f32_e32 v3, v6, v109
	v_exp_f32_e32 v202, v3
	v_sub_f32_e32 v3, v4, v109
	v_exp_f32_e32 v116, v3
	v_sub_f32_e32 v3, v8, v109
	v_exp_f32_e32 v120, v3
	v_sub_f32_e32 v3, v9, v109
	v_exp_f32_e32 v203, v3
	v_sub_f32_e32 v3, v10, v109
	v_exp_f32_e32 v204, v3
	v_sub_f32_e32 v3, v11, v109
	v_exp_f32_e32 v122, v3
	v_sub_f32_e32 v3, v12, v109
	v_exp_f32_e32 v92, v3
	v_sub_f32_e32 v3, v13, v109
	v_exp_f32_e32 v205, v3
	v_sub_f32_e32 v3, v14, v109
	v_exp_f32_e32 v206, v3
	v_sub_f32_e32 v3, v15, v109
	v_exp_f32_e32 v94, v3
	v_sub_f32_e32 v3, v91, v109
	v_exp_f32_e32 v108, v3
	v_sub_f32_e32 v3, v112, v109
	v_exp_f32_e32 v207, v3
	v_sub_f32_e32 v3, v113, v109
	v_exp_f32_e32 v208, v3
	v_sub_f32_e32 v3, v114, v109
	v_sub_f32_e32 v22, v22, v109
	v_exp_f32_e32 v112, v3
	v_sub_f32_e32 v3, v115, v109
	v_exp_f32_e32 v22, v22
	v_sub_f32_e32 v26, v29, v109
	v_exp_f32_e32 v76, v3
	v_sub_f32_e32 v3, v117, v109
	v_exp_f32_e32 v83, v24
	v_exp_f32_e32 v196, v26
	v_sub_f32_e32 v26, v30, v109
	v_exp_f32_e32 v209, v3
	v_sub_f32_e32 v3, v118, v109
	v_sub_f32_e32 v21, v21, v109
	v_exp_f32_e32 v197, v26
	v_exp_f32_e32 v210, v3
	v_sub_f32_e32 v3, v119, v109
	v_add_f32_e32 v69, 0, v18
	v_exp_f32_e32 v21, v21
	v_exp_f32_e32 v78, v3
	v_sub_f32_e32 v3, v121, v109
	v_add_f32_e32 v24, v22, v69
	v_exp_f32_e32 v90, v3
	v_sub_f32_e32 v3, v123, v109
	v_add_f32_e32 v24, v83, v24
	v_exp_f32_e32 v211, v3
	v_sub_f32_e32 v3, v124, v109
	v_add_f32_e32 v68, 0, v17
	v_add_f32_e32 v1, v197, v24
	v_exp_f32_e32 v212, v3
	v_sub_f32_e32 v3, v125, v109
	v_add_f32_e32 v68, v21, v68
	v_add_f32_e32 v1, v200, v1
	v_exp_f32_e32 v110, v3
	v_sub_f32_e32 v3, v126, v109
	v_add_f32_e32 v25, v82, v68
	v_add_f32_e32 v1, v202, v1
	v_exp_f32_e32 v68, v3
	v_sub_f32_e32 v3, v127, v109
	v_add_f32_e32 v1, v204, v1
	v_exp_f32_e32 v213, v3
	v_sub_f32_e32 v3, v128, v109
	v_add_f32_e32 v1, v206, v1
	v_exp_f32_e32 v214, v3
	v_add_f32_e32 v1, v208, v1
	v_add_f32_e32 v1, v210, v1
	v_add_f32_e32 v1, v212, v1
	v_add_f32_e32 v74, v214, v1
	v_sub_f32_e32 v1, v109, v7
	v_exp_f32_e32 v136, v1
	v_sub_f32_e32 v1, v45, v7
	v_sub_f32_e32 v3, v129, v109
	v_exp_f32_e32 v109, v1
	v_sub_f32_e32 v1, v46, v7
	v_exp_f32_e32 v130, v1
	v_sub_f32_e32 v1, v47, v7
	v_exp_f32_e32 v131, v1
	v_sub_f32_e32 v1, v48, v7
	v_exp_f32_e32 v79, v1
	v_sub_f32_e32 v1, v49, v7
	v_exp_f32_e32 v77, v1
	v_sub_f32_e32 v1, v50, v7
	v_add_f32_e32 v25, v196, v25
	v_exp_f32_e32 v124, v1
	v_sub_f32_e32 v1, v51, v7
	v_add_f32_e32 v2, v199, v25
	v_exp_f32_e32 v125, v1
	v_sub_f32_e32 v1, v52, v7
	v_add_f32_e32 v2, v201, v2
	v_exp_f32_e32 v111, v1
	v_sub_f32_e32 v1, v53, v7
	v_add_f32_e32 v2, v203, v2
	v_sub_f32_e32 v4, v31, v7
	v_exp_f32_e32 v91, v1
	v_sub_f32_e32 v1, v54, v7
	v_add_f32_e32 v2, v205, v2
	v_exp_f32_e32 v117, v4
	v_sub_f32_e32 v4, v34, v7
	v_exp_f32_e32 v126, v1
	v_sub_f32_e32 v1, v55, v7
	v_add_f32_e32 v2, v207, v2
	v_exp_f32_e32 v132, v4
	v_sub_f32_e32 v4, v35, v7
	v_exp_f32_e32 v127, v1
	v_sub_f32_e32 v1, v56, v7
	v_add_f32_e32 v2, v209, v2
	v_exp_f32_e32 v133, v4
	v_sub_f32_e32 v4, v36, v7
	v_exp_f32_e32 v71, v1
	v_sub_f32_e32 v1, v57, v7
	v_add_f32_e32 v2, v211, v2
	v_exp_f32_e32 v123, v4
	v_sub_f32_e32 v4, v37, v7
	v_exp_f32_e32 v69, v1
	v_sub_f32_e32 v1, v58, v7
	v_exp_f32_e32 v121, v4
	v_sub_f32_e32 v4, v38, v7
	v_add_f32_e32 v72, v213, v2
	v_sub_f32_e32 v2, v41, v7
	v_exp_f32_e32 v114, v1
	v_sub_f32_e32 v1, v59, v7
	v_exp_f32_e32 v134, v4
	v_sub_f32_e32 v4, v39, v7
	v_exp_f32_e32 v93, v2
	v_sub_f32_e32 v2, v42, v7
	v_exp_f32_e32 v115, v1
	v_sub_f32_e32 v1, v60, v7
	v_exp_f32_e32 v135, v4
	v_exp_f32_e32 v128, v2
	v_sub_f32_e32 v2, v43, v7
	v_exp_f32_e32 v75, v1
	v_sub_f32_e32 v1, v61, v7
	v_exp_f32_e32 v70, v3
	v_sub_f32_e32 v3, v40, v7
	v_exp_f32_e32 v129, v2
	v_exp_f32_e32 v73, v1
	v_sub_f32_e32 v1, v62, v7
	v_exp_f32_e32 v95, v3
	v_sub_f32_e32 v2, v44, v7
	v_exp_f32_e32 v118, v1
	v_sub_f32_e32 v1, v63, v7
	v_exp_f32_e32 v113, v2
	v_exp_f32_e32 v119, v1
	v_pk_add_f32 v[2:3], v[132:133], 0 op_sel_hi:[1,0]
	v_mov_b32_e32 v1, v169
	v_pk_add_f32 v[2:3], v[134:135], v[2:3]
	v_pk_add_f32 v[0:1], v[116:117], v[0:1]
	v_pk_add_f32 v[2:3], v[128:129], v[2:3]
	v_pk_add_f32 v[4:5], v[122:123], v[32:33]
	v_pk_add_f32 v[0:1], v[120:121], v[0:1]
	v_pk_add_f32 v[2:3], v[130:131], v[2:3]
	v_pk_add_f32 v[4:5], v[94:95], v[4:5]
	v_pk_add_f32 v[0:1], v[92:93], v[0:1]
	v_pk_add_f32 v[2:3], v[124:125], v[2:3]
	v_pk_add_f32 v[4:5], v[112:113], v[4:5]
	v_pk_add_f32 v[0:1], v[108:109], v[0:1]
	v_pk_add_f32 v[2:3], v[126:127], v[2:3]
	v_pk_add_f32 v[4:5], v[78:79], v[4:5]
	v_pk_add_f32 v[0:1], v[76:77], v[0:1]
	v_pk_add_f32 v[2:3], v[114:115], v[2:3]
	v_pk_add_f32 v[4:5], v[110:111], v[4:5]
	v_pk_add_f32 v[0:1], v[90:91], v[0:1]
	v_pk_add_f32 v[2:3], v[118:119], v[2:3]
	v_pk_add_f32 v[4:5], v[70:71], v[4:5]
	v_pk_add_f32 v[0:1], v[68:69], v[0:1]
	v_pk_add_f32 v[2:3], v[2:3], v[2:3] op_sel_hi:[0,1]
	v_pk_add_f32 v[4:5], v[74:75], v[4:5]
	v_pk_add_f32 v[0:1], v[72:73], v[0:1]
	v_mov_b32_e32 v2, v169
	v_pk_add_f32 v[0:1], v[4:5], v[0:1]
	v_lshl_add_u64 v[64:65], vcc, 0, v[168:169]
	v_pk_add_f32 v[0:1], v[0:1], v[2:3]
	v_add_u32_e32 v72, v152, v153
	v_fmac_f32_e32 v1, v0, v136
	ds_bpermute_b32 v0, v157, v1
	v_add_u32_e32 v74, v152, v154
	v_and_b32_e32 v52, 0xfffff800, v86
	v_bfe_u32 v54, v86, 4, 7
	v_cvt_pk_bf16_f32 v60, v81, v82
	s_waitcnt lgkmcnt(0)
; __device__ __forceinline__ int tpos(int t) { return (t & ~2047) | ((t & 15) << 7) | ((t & 2047) >> 4); }
; __device__ __forceinline__ void attn_load(const bf16_t* proj, const AttnItem& t, u32x4 (&kv)[6], u32x4 (&vv)[6], int tid) {
;     const int nb0 = t.nb & ~1;
;     const bf16_t* kb = proj + (size_t)NB * NH * SEQ * HD + (size_t)(t.b * NH + t.h) * SEQ * 2 * HD;
; #pragma unroll
;     for (int c = 0; c < 6; ++c) { const int idx = tid + 512 * c, j = idx >> 3, ch = idx & 7; const int sidx = (nb0 - 1) * 128 + j;
;         const int sj = sidx >= 0 ? sidx : sidx + 128;
;         const bf16_t* p = kb + (size_t)tpos(sj * t.dil + t.r) * 2 * HD + ch * 8; kv[c] = *(const u32x4*)p; vv[c] = *(const u32x4*)(p + HD); }
; }
; template <bool FINAL>
; __device__ __forceinline__ void attn_compute(LAS unsigned char* lds, const bf16_t* proj, const AttnItem& t, const AttnItem& nxt, bool more, bf16x8 (&qf)[4], bf16_t* o23, float* lse23, bf16_t* ycat, int lane, int wid) {
;     ...
;     const float lse = mx + __builtin_amdgcn_logf(l);
;     if (!FINAL) {
;         const float c1 = 1.0f / l;
;         if (hi == 0) lse23[(size_t)t.br * M * NH + hrow] = lse;
;         bf16_t* ob = o23 + ((size_t)t.br * M * NH + hrow) * HD + 8 * hi;
; #pragma unroll
;         for (int d = 0; d < 2; ++d)
; #pragma unroll
;             for (int g = 0; g < 4; g += 2) { u32x2 wa, wb;
;                 wa.x = cvt_pk_bf16(o[d][4 * g] * c1, o[d][4 * g + 1] * c1); wa.y = cvt_pk_bf16(o[d][4 * g + 2] * c1, o[d][4 * g + 3] * c1);
;                 wb.x = cvt_pk_bf16(o[d][4 * g + 4] * c1, o[d][4 * g + 5] * c1); wb.y = cvt_pk_bf16(o[d][4 * g + 6] * c1, o[d][4 * g + 7] * c1);
;                 *(u32x4*)(ob + 32 * d + 8 * g) = pair16(wa, wb); }
;     } else {
;         const float mm = fmaxf(lse, fmaxf(l2, l3));
;         const float e1 = __builtin_amdgcn_exp2f(lse - mm), e2 = __builtin_amdgcn_exp2f(l2 - mm), e3 = __builtin_amdgcn_exp2f(l3 - mm);
;         const float inv = 1.0f / (e1 + e2 + e3);
;         const float c1 = e1 * inv / l, c2 = e2 * inv, c3 = e3 * inv;
	v_add_f32_e32 v168, v1, v0
	v_log_f32_e32 v0, v168
	v_cvt_pk_bf16_f32 v61, v83, v192
	v_cvt_pk_bf16_f32 v62, v195, v196
	v_cvt_pk_bf16_f32 v63, v197, v193
	v_add_f32_e32 v0, v7, v0
	s_waitcnt vmcnt(0)
	v_max3_f32 v1, v0, v27, v80
	v_sub_f32_e32 v0, v0, v1
	v_sub_f32_e32 v2, v27, v1
	v_exp_f32_e32 v0, v0
	v_exp_f32_e32 v189, v2
	v_sub_f32_e32 v1, v80, v1
	v_exp_f32_e32 v190, v1
	v_cvt_pk_bf16_f32 v7, v22, v23
	v_add_f32_e32 v1, v0, v189
	v_cvt_pk_bf16_f32 v196, v120, v203
	v_add_f32_e32 v1, v190, v1
	v_div_scale_f32 v2, s[24:25], v1, v1, 1.0
	v_rcp_f32_e32 v3, v2
	v_cvt_pk_bf16_f32 v197, v204, v122
	v_lshl_add_u64 v[64:65], v[96:97], 1, v[64:65]
	v_fma_f32 v4, -v2, v3, 1.0
	v_fmac_f32_e32 v3, v4, v3
	v_div_scale_f32 v4, vcc, 1.0, v1, 1.0
	v_mul_f32_e32 v5, v4, v3
	v_fma_f32 v6, -v2, v5, v4
	v_fmac_f32_e32 v5, v6, v3
	v_fma_f32 v2, -v2, v5, v4
	v_div_fmas_f32 v2, v2, v3, v5
	v_div_fixup_f32 v191, v2, v1, 1.0
	v_mul_f32_e32 v215, v0, v191
	v_div_scale_f32 v0, s[24:25], v168, v168, v215
	v_rcp_f32_e32 v1, v0
	v_cvt_pk_bf16_f32 v5, v18, v19
	v_cvt_pk_bf16_f32 v6, v20, v21
	s_lshl_b64 s[24:25], s[98:99], 24
	v_fma_f32 v2, -v0, v1, 1.0
	v_fmac_f32_e32 v1, v2, v1
	v_div_scale_f32 v2, vcc, v215, v168, v215
	v_mul_f32_e32 v3, v2, v1
	v_fma_f32 v4, -v0, v3, v2
	v_fmac_f32_e32 v3, v4, v1
	v_fma_f32 v0, -v0, v3, v2
	v_div_fmas_f32 v216, v0, v1, v3
	v_lshlrev_b32_e32 v1, 7, v187
	v_and_b32_e32 v0, 0xfffff800, v187
	v_and_b32_e32 v1, 0x780, v1
	v_bfe_u32 v2, v187, 4, 7
	v_or3_b32 v0, v1, v0, v2
	v_ashrrev_i32_e32 v1, 31, v0
	v_lshlrev_b64 v[0:1], 8, v[0:1]
	v_lshl_add_u64 v[0:1], v[88:89], 0, v[0:1]
	global_load_dwordx4 v[32:35], v[0:1], off
	global_load_dwordx4 v[36:39], v[0:1], off offset:128
	v_lshlrev_b32_e32 v1, 7, v87
	v_and_b32_e32 v0, 0xfffff800, v87
	v_and_b32_e32 v1, 0x780, v1
	v_bfe_u32 v2, v87, 4, 7
	v_or3_b32 v0, v1, v0, v2
	v_ashrrev_i32_e32 v1, 31, v0
	v_lshlrev_b64 v[0:1], 8, v[0:1]
	v_lshl_add_u64 v[12:13], v[88:89], 0, v[0:1]
	ds_read_b64_tr_b16 v[0:1], v72 offset:49152
	ds_read_b64_tr_b16 v[2:3], v72 offset:50176
	global_load_dwordx4 v[40:43], v[12:13], off
	v_cvt_pk_bf16_f32 v4, v16, v17
	ds_read_b64_tr_b16 v[8:9], v74 offset:49152
	ds_read_b64_tr_b16 v[10:11], v74 offset:50176
	s_waitcnt lgkmcnt(2)
	v_mfma_f32_32x32x16_bf16 v[16:31], v[0:3], v[4:7], 0
	global_load_dwordx4 v[44:47], v[12:13], off offset:128
	v_lshlrev_b32_e32 v0, 7, v86
	ds_read_b64_tr_b16 v[48:49], v72 offset:51200
	ds_read_b64_tr_b16 v[50:51], v72 offset:52224
	v_and_b32_e32 v53, 0x780, v0
	v_or3_b32 v52, v53, v52, v54
	ds_read_b64_tr_b16 v[56:57], v74 offset:51200
	ds_read_b64_tr_b16 v[58:59], v74 offset:52224
	v_ashrrev_i32_e32 v53, 31, v52
	s_waitcnt lgkmcnt(4)
	v_mfma_f32_32x32x16_bf16 v[0:15], v[8:11], v[4:7], 0
	v_and_b32_e32 v86, 0xfffff800, v85
	s_add_u32 s24, s26, s24
	s_addc_u32 s25, s27, s25
	s_lshl_b32 s12, s12, 7
	s_cmp_lg_u32 s15, s17
	s_mov_b32 s98, s20
	s_waitcnt lgkmcnt(2)
	v_mfma_f32_32x32x16_bf16 v[16:31], v[48:51], v[60:63], v[16:31]
	v_lshlrev_b64 v[48:49], 8, v[52:53]
	v_lshl_add_u64 v[52:53], v[88:89], 0, v[48:49]
	global_load_dwordx4 v[48:51], v[52:53], off
	s_nop 0
	global_load_dwordx4 v[52:55], v[52:53], off offset:128
	ds_read_b64_tr_b16 v[80:81], v72 offset:53248
	ds_read_b64_tr_b16 v[82:83], v72 offset:54272
	s_waitcnt lgkmcnt(2)
	v_mfma_f32_32x32x16_bf16 v[0:15], v[56:59], v[60:63], v[0:15]
	v_cvt_pk_bf16_f32 v56, v198, v199
	v_cvt_pk_bf16_f32 v57, v200, v194
	ds_read_b64_tr_b16 v[60:61], v74 offset:53248
	ds_read_b64_tr_b16 v[62:63], v74 offset:54272
	v_cvt_pk_bf16_f32 v58, v116, v201
	v_cvt_pk_bf16_f32 v59, v202, v66
	v_lshlrev_b32_e32 v66, 7, v85
	v_and_b32_e32 v66, 0x780, v66
	s_waitcnt lgkmcnt(2)
	v_mfma_f32_32x32x16_bf16 v[16:31], v[80:83], v[56:59], v[16:31]
	v_bfe_u32 v80, v85, 4, 7
	v_or3_b32 v86, v66, v86, v80
	ds_read_b64_tr_b16 v[80:81], v72 offset:55296
	ds_read_b64_tr_b16 v[82:83], v72 offset:56320
	ds_read_b64_tr_b16 v[192:193], v74 offset:55296
	ds_read_b64_tr_b16 v[194:195], v74 offset:56320
	v_cvt_pk_bf16_f32 v198, v92, v205
	v_cvt_pk_bf16_f32 v199, v206, v94
	v_ashrrev_i32_e32 v87, 31, v86
	s_waitcnt lgkmcnt(4)
	v_mfma_f32_32x32x16_bf16 v[0:15], v[60:63], v[56:59], v[0:15]
	v_lshlrev_b64 v[56:57], 8, v[86:87]
	v_lshl_add_u64 v[60:61], v[88:89], 0, v[56:57]
	global_load_dwordx4 v[56:59], v[60:61], off
	s_nop 0
	global_load_dwordx4 v[60:63], v[60:61], off offset:128
	v_lshlrev_b32_e32 v85, 7, v84
	v_and_b32_e32 v66, 0xfffff800, v84
	v_and_b32_e32 v85, 0x780, v85
	v_cvt_pk_bf16_f32 v92, v95, v93
	s_waitcnt lgkmcnt(2)
	v_mfma_f32_32x32x16_bf16 v[16:31], v[80:83], v[196:199], v[16:31]
	ds_read_b64_tr_b16 v[80:81], v72 offset:57344
	ds_read_b64_tr_b16 v[82:83], v72 offset:58368
	v_cvt_pk_bf16_f32 v93, v128, v129
	v_cvt_pk_bf16_f32 v94, v113, v109
	v_cvt_pk_bf16_f32 v95, v130, v131
	s_waitcnt lgkmcnt(2)
	v_mfma_f32_32x32x16_bf16 v[0:15], v[192:195], v[196:199], v[0:15]
	ds_read_b64_tr_b16 v[192:193], v74 offset:57344
	ds_read_b64_tr_b16 v[194:195], v74 offset:58368
	v_cvt_pk_bf16_f32 v196, v108, v207
	v_cvt_pk_bf16_f32 v197, v208, v112
	v_cvt_pk_bf16_f32 v198, v76, v209
	v_cvt_pk_bf16_f32 v199, v210, v78
	v_bfe_u32 v76, v84, 4, 7
	v_cvt_pk_bf16_f32 v78, v111, v91
	s_waitcnt lgkmcnt(2)
	v_mfma_f32_32x32x16_bf16 v[16:31], v[80:83], v[196:199], v[16:31]
	v_or3_b32 v80, v85, v66, v76
	ds_read_b64_tr_b16 v[84:85], v72 offset:59392
	ds_read_b64_tr_b16 v[86:87], v72 offset:60416
	v_ashrrev_i32_e32 v81, 31, v80
	v_lshlrev_b64 v[80:81], 8, v[80:81]
	v_lshl_add_u64 v[200:201], v[88:89], 0, v[80:81]
	global_load_dwordx4 v[80:83], v[200:201], off
	v_add_u32_e32 v72, v156, v154
	s_waitcnt lgkmcnt(2)
; #define LAS __attribute__((address_space(3)))
; __device__ __forceinline__ s16x4 vtr(LAS const unsigned char* p) { return __builtin_bit_cast(s16x4, __builtin_amdgcn_ds_read_tr16_b64_v4i16((LAS v4i16_t*)p)); }
; template <int T0, int NT, bool FIRST>
; __device__ __forceinline__ void attn_group(LAS const unsigned char* Kl, LAS const unsigned char* Vl, const bf16x8 (&qf)[4], f32x16 (&o)[2], float& mx, float& l, int nb, int w, int lane) {
;     ...
;     else { const float mn = fmaxf(mx, gm); const float f = __builtin_amdgcn_exp2f(mx - mn); l *= f; mx = mn;
; #pragma unroll
;         for (int d = 0; d < 2; ++d)
; #pragma unroll
;             for (int i = 0; i < 16; ++i) o[d][i] *= f; }
;     ...
; #pragma unroll
;     for (int t = 0; t < NT; ++t)
; #pragma unroll
;         for (int s2 = 0; s2 < 2; ++s2) {
;             u32x4 pw; pw.x = cvt_pk_bf16(s[t][8 * s2 + 0], s[t][8 * s2 + 1]); pw.y = cvt_pk_bf16(s[t][8 * s2 + 2], s[t][8 * s2 + 3]);
;             pw.z = cvt_pk_bf16(s[t][8 * s2 + 4], s[t][8 * s2 + 5]); pw.w = cvt_pk_bf16(s[t][8 * s2 + 6], s[t][8 * s2 + 7]);
;             const bf16x8 pf = __builtin_bit_cast(bf16x8, pw);
; #pragma unroll
;             for (int d = 0; d < 2; ++d) {
;                 LAS const unsigned char* vp = vb + (t * 32 + s2 * 16) * 128 + ((d * 64) ^ vsw);
;                 const s16x4 lo = vtr(vp), hi4 = vtr(vp + 8 * 128);
;                 const bf16x8 vf = (bf16x8){lo[0], lo[1], lo[2], lo[3], hi4[0], hi4[1], hi4[2], hi4[3]};
;                 o[d] = __builtin_amdgcn_mfma_f32_32x32x16_bf16(vf, pf, o[d], 0, 0, 0);
;             }
;         }
; }
	v_mfma_f32_32x32x16_bf16 v[0:15], v[192:195], v[196:199], v[0:15]
	ds_read_b64_tr_b16 v[192:193], v74 offset:59392
	ds_read_b64_tr_b16 v[194:195], v74 offset:60416
	v_cvt_pk_bf16_f32 v196, v90, v211
	v_cvt_pk_bf16_f32 v197, v212, v110
	v_cvt_pk_bf16_f32 v198, v68, v213
	v_cvt_pk_bf16_f32 v199, v214, v70
	v_add_u32_e32 v70, v156, v153
	v_lshlrev_b32_e32 v68, 7, v186
	s_waitcnt lgkmcnt(2)
	v_mfma_f32_32x32x16_bf16 v[16:31], v[84:87], v[196:199], v[16:31]
	global_load_dwordx4 v[84:87], v[200:201], off offset:128
	s_nop 0
	v_mov_b32_e32 v200, v220
	v_mov_b32_e32 v201, v221
	v_mov_b32_e32 v202, v230
	v_mov_b32_e32 v203, v231
	v_mov_b32_e32 v204, v218
	v_mov_b32_e32 v205, v219
	v_and_b32_e32 v66, 0xfffff800, v186
	v_and_b32_e32 v68, 0x780, v68
	v_cvt_pk_bf16_f32 v76, v79, v77
	v_cvt_pk_bf16_f32 v77, v124, v125
	v_cvt_pk_bf16_f32 v79, v126, v127
	s_waitcnt lgkmcnt(0)
	v_mfma_f32_32x32x16_bf16 v[0:15], v[192:195], v[196:199], v[0:15]
	ds_read_b64_tr_b16 v[192:193], v70 offset:49152
	ds_read_b64_tr_b16 v[194:195], v70 offset:50176
	v_mul_f32_e64 v30, v30, v136
	v_mul_f32_e64 v31, v31, v136
	v_mul_f32_e64 v28, v28, v136
	v_mul_f32_e64 v29, v29, v136
	v_pk_mul_f32 v[26:27], v[26:27], v[136:137] op_sel_hi:[1,0]
	v_pk_mul_f32 v[24:25], v[24:25], v[136:137] op_sel_hi:[1,0]
	v_pk_mul_f32 v[22:23], v[22:23], v[136:137] op_sel_hi:[1,0]
	v_pk_mul_f32 v[20:21], v[20:21], v[136:137] op_sel_hi:[1,0]
	v_pk_mul_f32 v[18:19], v[18:19], v[136:137] op_sel_hi:[1,0]
	v_pk_mul_f32 v[16:17], v[16:17], v[136:137] op_sel_hi:[1,0]
	v_cvt_pk_bf16_f32 v196, v67, v117
	v_cvt_pk_bf16_f32 v197, v132, v133
	v_cvt_pk_bf16_f32 v198, v123, v121
	v_cvt_pk_bf16_f32 v199, v134, v135
	ds_read_b64_tr_b16 v[120:121], v72 offset:49152
	ds_read_b64_tr_b16 v[122:123], v72 offset:50176
	s_waitcnt lgkmcnt(2)
	v_mfma_f32_32x32x16_bf16 v[16:31], v[192:195], v[196:199], v[16:31]
	ds_read_b64_tr_b16 v[132:133], v70 offset:51200
	ds_read_b64_tr_b16 v[134:135], v70 offset:52224
	v_mov_b32_e32 v116, v232
	v_mov_b32_e32 v117, v233
	v_mul_f32_e64 v14, v14, v136
	v_mul_f32_e64 v15, v15, v136
	v_pk_mul_f32 v[12:13], v[12:13], v[136:137] op_sel_hi:[1,0]
	v_pk_mul_f32 v[10:11], v[10:11], v[136:137] op_sel_hi:[1,0]
	v_pk_mul_f32 v[8:9], v[8:9], v[136:137] op_sel_hi:[1,0]
	v_pk_mul_f32 v[6:7], v[6:7], v[136:137] op_sel_hi:[1,0]
	v_pk_mul_f32 v[4:5], v[4:5], v[136:137] op_sel_hi:[1,0]
	v_pk_mul_f32 v[2:3], v[2:3], v[136:137] op_sel_hi:[1,0]
	v_pk_mul_f32 v[0:1], v[0:1], v[136:137] op_sel_hi:[1,0]
	s_waitcnt lgkmcnt(0)
	v_mfma_f32_32x32x16_bf16 v[16:31], v[132:135], v[92:95], v[16:31]
	v_bfe_u32 v67, v186, 4, 7
	v_or3_b32 v66, v68, v66, v67
	v_ashrrev_i32_e32 v67, 31, v66
	v_lshlrev_b64 v[66:67], 8, v[66:67]
	v_lshl_add_u64 v[66:67], v[88:89], 0, v[66:67]
	v_cvt_pk_bf16_f32 v68, v75, v73
	v_mul_f32_e32 v112, v189, v191
	v_mfma_f32_32x32x16_bf16 v[0:15], v[120:123], v[196:199], v[0:15]
	ds_read_b64_tr_b16 v[120:121], v72 offset:51200
	ds_read_b64_tr_b16 v[122:123], v72 offset:52224
	v_mov_b32_e32 v132, v234
	v_mov_b32_e32 v133, v235
	ds_read_b64_tr_b16 v[128:129], v70 offset:53248
	ds_read_b64_tr_b16 v[130:131], v70 offset:54272
	v_mov_b32_e32 v134, v236
	v_mov_b32_e32 v135, v237
	ds_read_b64_tr_b16 v[108:109], v72 offset:53248
	ds_read_b64_tr_b16 v[110:111], v72 offset:54272
	v_and_b32_e32 v189, 0xffff0000, v200
	s_waitcnt lgkmcnt(4)
	v_mfma_f32_32x32x16_bf16 v[0:15], v[120:123], v[92:95], v[0:15]
	global_load_dwordx4 v[88:91], v[66:67], off
	global_load_dwordx4 v[92:95], v[66:67], off offset:128
	v_mov_b32_e32 v124, v238
	v_mov_b32_e32 v125, v239
	v_mov_b32_e32 v126, v240
	v_mov_b32_e32 v127, v241
	ds_read_b64_tr_b16 v[120:121], v70 offset:55296
	ds_read_b64_tr_b16 v[122:123], v70 offset:56320
	v_cvt_pk_bf16_f32 v66, v71, v69
	v_cvt_pk_bf16_f32 v67, v114, v115
	v_cvt_pk_bf16_f32 v69, v118, v119
	v_div_fixup_f32 v114, v216, v168, v215
	v_lshlrev_b32_e32 v168, 11, v188
	s_waitcnt lgkmcnt(4)
	v_mfma_f32_32x32x16_bf16 v[16:31], v[128:131], v[76:79], v[16:31]
	v_mov_b32_e32 v128, v242
	v_mov_b32_e32 v129, v243
	v_lshlrev_b32_e32 v188, 16, v200
	s_waitcnt lgkmcnt(2)
	v_mfma_f32_32x32x16_bf16 v[0:15], v[108:111], v[76:79], v[0:15]
	ds_read_b64_tr_b16 v[76:77], v72 offset:55296
	ds_read_b64_tr_b16 v[78:79], v72 offset:56320
	v_mul_f32_e32 v110, v190, v191
	v_lshl_add_u64 v[108:109], s[24:25], 0, v[168:169]
	v_lshl_add_u64 v[108:109], v[108:109], 0, s[12:13]
	v_lshl_add_u64 v[108:109], v[102:103], 1, v[108:109]
	s_mov_b32 s12, s21
	s_waitcnt lgkmcnt(2)
	v_mfma_f32_32x32x16_bf16 v[16:31], v[120:123], v[66:69], v[16:31]
	v_mov_b32_e32 v118, v246
	v_mov_b32_e32 v119, v247
	v_mov_b32_e32 v120, v254
	v_mov_b32_e32 v121, v255
	s_nop 0
	global_load_dwordx2 v[106:107], v[106:107], off offset:112
	s_nop 0
	v_mov_b32_e32 v122, v244
	v_mov_b32_e32 v123, v245
	v_mov_b32_e32 v130, v248
	v_mov_b32_e32 v131, v249
	global_load_dwordx2 v[186:187], v[104:105], off offset:96
	s_nop 0
	global_load_dwordx2 v[104:105], v[104:105], off offset:112
	s_nop 1
	v_pk_mul_f32 v[16:17], v[16:17], v[114:115] op_sel_hi:[1,0]
	s_waitcnt lgkmcnt(0)
; __device__ __forceinline__ float bf_lo(unsigned u) { return __uint_as_float(u << 16); }
; __device__ __forceinline__ float bf_hi(unsigned u) { return __uint_as_float(u & 0xffff0000u); }
; __device__ __forceinline__ int tpos(int t) { return (t & ~2047) | ((t & 15) << 7) | ((t & 2047) >> 4); }
; __device__ __forceinline__ void attn_load_q(const bf16_t* proj, const AttnItem& t, bf16x8 (&qf)[4], int lane, int wid) {
;     const int w = wid & 3, r32 = lane & 31, hi = lane >> 5;
;     const size_t qrow = (size_t)(t.b * NH + t.h) * SEQ + tpos((t.nb * 128 + 32 * w + r32) * t.dil + t.r);
; #pragma unroll
;     for (int ks = 0; ks < 4; ++ks) qf[ks] = *(const bf16x8*)(proj + qrow * HD + 16 * ks + 8 * hi);
; template <bool FINAL>
; __device__ __forceinline__ void attn_compute(LAS unsigned char* lds, const bf16_t* proj, const AttnItem& t, const AttnItem& nxt, bool more, bf16x8 (&qf)[4], bf16_t* o23, float* lse23, bf16_t* ycat, int lane, int wid) {
;     ...
;         bf16_t* yo = ycat + qrow * DM + t.h * HD + 8 * hi;
; #pragma unroll
;         for (int d = 0; d < 2; ++d)
; #pragma unroll
;             for (int g = 0; g < 4; g += 2) { u32x2 wp[2];
; #pragma unroll
;                 for (int e = 0; e < 2; ++e) { const int gg = g + e; const u32x2 b2 = a2[4 * d + gg], b3 = a3[4 * d + gg];
;                     wp[e].x = cvt_pk_bf16(c1 * o[d][4 * gg] + c2 * bf_lo(b2.x) + c3 * bf_lo(b3.x), c1 * o[d][4 * gg + 1] + c2 * bf_hi(b2.x) + c3 * bf_hi(b3.x));
;                     wp[e].y = cvt_pk_bf16(c1 * o[d][4 * gg + 2] + c2 * bf_lo(b2.y) + c3 * bf_lo(b3.y), c1 * o[d][4 * gg + 3] + c2 * bf_hi(b2.y) + c3 * bf_hi(b3.y)); }
;                 *(u32x4*)(yo + 32 * d + 8 * g) = pair16(wp[0], wp[1]); }
	v_mfma_f32_32x32x16_bf16 v[0:15], v[76:79], v[66:69], v[0:15]
	global_load_dwordx4 v[76:79], v[64:65], off
	global_load_dwordx4 v[72:75], v[64:65], off offset:32
	global_load_dwordx4 v[68:71], v[64:65], off offset:64
	s_nop 0
	global_load_dwordx4 v[64:67], v[64:65], off offset:96
	v_fma_f32 v16, v112, v188, v16
	v_fma_f32 v17, v112, v189, v17
	v_lshlrev_b32_e32 v188, 16, v204
	v_and_b32_e32 v189, 0xffff0000, v204
	v_pk_fma_f32 v[16:17], v[110:111], v[188:189], v[16:17] op_sel_hi:[0,1,1]
	v_pk_mul_f32 v[18:19], v[18:19], v[114:115] op_sel_hi:[1,0]
	v_lshlrev_b32_e32 v188, 16, v201
	v_and_b32_e32 v189, 0xffff0000, v201
	v_pk_fma_f32 v[18:19], v[112:113], v[188:189], v[18:19] op_sel_hi:[0,1,1]
	v_lshlrev_b32_e32 v188, 16, v205
	v_and_b32_e32 v189, 0xffff0000, v205
	v_pk_fma_f32 v[18:19], v[110:111], v[188:189], v[18:19] op_sel_hi:[0,1,1]
	v_cvt_pk_bf16_f32 v16, v16, v17
	v_cvt_pk_bf16_f32 v17, v18, v19
	v_pk_mul_f32 v[18:19], v[20:21], v[114:115] op_sel_hi:[1,0]
	v_lshlrev_b32_e32 v20, 16, v202
	v_and_b32_e32 v21, 0xffff0000, v202
	v_pk_fma_f32 v[18:19], v[112:113], v[20:21], v[18:19] op_sel_hi:[0,1,1]
	v_lshlrev_b32_e32 v20, 16, v116
	v_and_b32_e32 v21, 0xffff0000, v116
	v_pk_fma_f32 v[18:19], v[110:111], v[20:21], v[18:19] op_sel_hi:[0,1,1]
	v_pk_mul_f32 v[20:21], v[22:23], v[114:115] op_sel_hi:[1,0]
	v_lshlrev_b32_e32 v22, 16, v203
	v_and_b32_e32 v23, 0xffff0000, v203
	v_pk_fma_f32 v[20:21], v[112:113], v[22:23], v[20:21] op_sel_hi:[0,1,1]
	v_lshlrev_b32_e32 v22, 16, v117
	v_and_b32_e32 v23, 0xffff0000, v117
	v_pk_fma_f32 v[20:21], v[110:111], v[22:23], v[20:21] op_sel_hi:[0,1,1]
	v_cvt_pk_bf16_f32 v18, v18, v19
	v_cvt_pk_bf16_f32 v19, v20, v21
	s_nop 0
	v_permlane32_swap_b32_e32 v16, v18
	v_permlane32_swap_b32_e32 v17, v19
	global_store_dwordx4 v[108:109], v[16:19], off
	v_lshlrev_b32_e32 v20, 16, v133
	v_and_b32_e32 v21, 0xffff0000, v133
	v_pk_mul_f32 v[16:17], v[24:25], v[114:115] op_sel_hi:[1,0]
	v_lshlrev_b32_e32 v18, 16, v132
	v_and_b32_e32 v19, 0xffff0000, v132
	v_pk_fma_f32 v[16:17], v[112:113], v[18:19], v[16:17] op_sel_hi:[0,1,1]
	v_lshlrev_b32_e32 v18, 16, v134
	v_and_b32_e32 v19, 0xffff0000, v134
	v_pk_fma_f32 v[16:17], v[110:111], v[18:19], v[16:17] op_sel_hi:[0,1,1]
	v_pk_mul_f32 v[18:19], v[26:27], v[114:115] op_sel_hi:[1,0]
	v_cvt_pk_bf16_f32 v16, v16, v17
	v_pk_fma_f32 v[18:19], v[112:113], v[20:21], v[18:19] op_sel_hi:[0,1,1]
	v_lshlrev_b32_e32 v20, 16, v135
	v_and_b32_e32 v21, 0xffff0000, v135
	v_pk_fma_f32 v[18:19], v[110:111], v[20:21], v[18:19] op_sel_hi:[0,1,1]
	v_cvt_pk_bf16_f32 v17, v18, v19
	v_pk_mul_f32 v[18:19], v[28:29], v[114:115] op_sel_hi:[1,0]
	v_lshlrev_b32_e32 v20, 16, v124
	v_and_b32_e32 v21, 0xffff0000, v124
	v_pk_fma_f32 v[18:19], v[112:113], v[20:21], v[18:19] op_sel_hi:[0,1,1]
	v_lshlrev_b32_e32 v20, 16, v126
	v_and_b32_e32 v21, 0xffff0000, v126
	v_pk_fma_f32 v[18:19], v[110:111], v[20:21], v[18:19] op_sel_hi:[0,1,1]
	v_pk_mul_f32 v[20:21], v[30:31], v[114:115] op_sel_hi:[1,0]
	v_lshlrev_b32_e32 v22, 16, v125
	v_and_b32_e32 v23, 0xffff0000, v125
	v_pk_fma_f32 v[20:21], v[112:113], v[22:23], v[20:21] op_sel_hi:[0,1,1]
	v_lshlrev_b32_e32 v22, 16, v127
	v_and_b32_e32 v23, 0xffff0000, v127
	v_pk_fma_f32 v[20:21], v[110:111], v[22:23], v[20:21] op_sel_hi:[0,1,1]
	v_cvt_pk_bf16_f32 v18, v18, v19
	v_cvt_pk_bf16_f32 v19, v20, v21
	s_nop 0
	v_permlane32_swap_b32_e32 v16, v18
	v_permlane32_swap_b32_e32 v17, v19
	global_store_dwordx4 v[108:109], v[16:19], off offset:32
	v_pk_mul_f32 v[0:1], v[0:1], v[114:115] op_sel_hi:[1,0]
	v_pk_mul_f32 v[2:3], v[2:3], v[114:115] op_sel_hi:[1,0]
	v_lshlrev_b32_e32 v16, 16, v128
	v_and_b32_e32 v17, 0xffff0000, v128
	v_pk_fma_f32 v[0:1], v[112:113], v[16:17], v[0:1] op_sel_hi:[0,1,1]
	v_lshlrev_b32_e32 v16, 16, v122
	v_and_b32_e32 v17, 0xffff0000, v122
	v_pk_fma_f32 v[0:1], v[110:111], v[16:17], v[0:1] op_sel_hi:[0,1,1]
	v_lshlrev_b32_e32 v16, 16, v129
	v_and_b32_e32 v17, 0xffff0000, v129
	v_pk_fma_f32 v[2:3], v[112:113], v[16:17], v[2:3] op_sel_hi:[0,1,1]
	v_lshlrev_b32_e32 v16, 16, v123
	v_and_b32_e32 v17, 0xffff0000, v123
	v_pk_fma_f32 v[2:3], v[110:111], v[16:17], v[2:3] op_sel_hi:[0,1,1]
	v_cvt_pk_bf16_f32 v0, v0, v1
	v_cvt_pk_bf16_f32 v1, v2, v3
	v_pk_mul_f32 v[2:3], v[4:5], v[114:115] op_sel_hi:[1,0]
	v_lshlrev_b32_e32 v4, 16, v118
	v_and_b32_e32 v5, 0xffff0000, v118
	v_pk_fma_f32 v[2:3], v[112:113], v[4:5], v[2:3] op_sel_hi:[0,1,1]
	v_lshlrev_b32_e32 v4, 16, v130
	v_and_b32_e32 v5, 0xffff0000, v130
	v_pk_fma_f32 v[2:3], v[110:111], v[4:5], v[2:3] op_sel_hi:[0,1,1]
	v_pk_mul_f32 v[4:5], v[6:7], v[114:115] op_sel_hi:[1,0]
	v_lshlrev_b32_e32 v6, 16, v119
	v_and_b32_e32 v7, 0xffff0000, v119
	v_pk_fma_f32 v[4:5], v[112:113], v[6:7], v[4:5] op_sel_hi:[0,1,1]
	v_lshlrev_b32_e32 v6, 16, v131
	v_and_b32_e32 v7, 0xffff0000, v131
	v_pk_fma_f32 v[4:5], v[110:111], v[6:7], v[4:5] op_sel_hi:[0,1,1]
	v_cvt_pk_bf16_f32 v2, v2, v3
	v_cvt_pk_bf16_f32 v3, v4, v5
	s_nop 0
	v_permlane32_swap_b32_e32 v0, v2
	v_permlane32_swap_b32_e32 v1, v3
	global_store_dwordx4 v[108:109], v[0:3], off offset:64
	v_lshlrev_b32_e32 v4, 16, v121
	v_and_b32_e32 v5, 0xffff0000, v121
	v_pk_mul_f32 v[0:1], v[8:9], v[114:115] op_sel_hi:[1,0]
	v_lshlrev_b32_e32 v2, 16, v120
	v_and_b32_e32 v3, 0xffff0000, v120
	v_pk_fma_f32 v[0:1], v[112:113], v[2:3], v[0:1] op_sel_hi:[0,1,1]
	s_waitcnt vmcnt(8)
	v_lshlrev_b32_e32 v2, 16, v186
	v_and_b32_e32 v3, 0xffff0000, v186
	v_pk_fma_f32 v[0:1], v[110:111], v[2:3], v[0:1] op_sel_hi:[0,1,1]
	v_pk_mul_f32 v[2:3], v[10:11], v[114:115] op_sel_hi:[1,0]
	v_cvt_pk_bf16_f32 v0, v0, v1
	v_pk_fma_f32 v[2:3], v[112:113], v[4:5], v[2:3] op_sel_hi:[0,1,1]
	v_lshlrev_b32_e32 v4, 16, v187
	v_and_b32_e32 v5, 0xffff0000, v187
	v_pk_fma_f32 v[2:3], v[110:111], v[4:5], v[2:3] op_sel_hi:[0,1,1]
	v_cvt_pk_bf16_f32 v1, v2, v3
	v_pk_mul_f32 v[2:3], v[12:13], v[114:115] op_sel_hi:[1,0]
	v_lshlrev_b32_e32 v4, 16, v106
	v_and_b32_e32 v5, 0xffff0000, v106
	v_pk_fma_f32 v[2:3], v[112:113], v[4:5], v[2:3] op_sel_hi:[0,1,1]
	s_waitcnt vmcnt(7)
	v_lshlrev_b32_e32 v4, 16, v104
	v_and_b32_e32 v5, 0xffff0000, v104
	v_pk_fma_f32 v[2:3], v[110:111], v[4:5], v[2:3] op_sel_hi:[0,1,1]
	v_pk_mul_f32 v[4:5], v[14:15], v[114:115] op_sel_hi:[1,0]
	v_lshlrev_b32_e32 v6, 16, v107
	v_and_b32_e32 v7, 0xffff0000, v107
	v_pk_fma_f32 v[4:5], v[112:113], v[6:7], v[4:5] op_sel_hi:[0,1,1]
	v_lshlrev_b32_e32 v6, 16, v105
	v_and_b32_e32 v7, 0xffff0000, v105
	v_pk_fma_f32 v[4:5], v[110:111], v[6:7], v[4:5] op_sel_hi:[0,1,1]
	v_cvt_pk_bf16_f32 v2, v2, v3
	v_cvt_pk_bf16_f32 v3, v4, v5
	s_nop 0
	v_permlane32_swap_b32_e32 v0, v2
	v_permlane32_swap_b32_e32 v1, v3
	global_store_dwordx4 v[108:109], v[0:3], off offset:96
	s_waitcnt lgkmcnt(0)
	s_barrier
; #define LAS __attribute__((address_space(3)))
; __device__ __forceinline__ void attn_stage(LAS unsigned char* lds, const u32x4 (&kv)[6], const u32x4 (&vv)[6], int tid, int wid) {
;     LAS unsigned char* Kl = lds; LAS unsigned char* Vl = lds + 49152;
; #pragma unroll
;     for (int c = 0; c < 6; ++c) { const int idx = tid + 512 * c, j = idx >> 3, ch = idx & 7;
;         *(LAS u32x4*)(Kl + j * 128 + ((ch ^ ((j >> 1) & 7)) * 16)) = kv[c];
;         *(LAS u32x4*)(Vl + j * 128 + (((ch >> 2) ^ ((j >> 1) & 1)) * 64) + (ch & 3) * 16) = vv[c]; }
; }
; template <bool FINAL>
; __device__ __forceinline__ void attn_phase(LAS unsigned char* lds, const bf16_t* proj, bf16_t* o23, float* lse23, bf16_t* ycat, int tid, int lane, int wid) {
;     ...
;         attn_stage(lds, kv, vv, tid, wid);
;         asm volatile("s_waitcnt lgkmcnt(0)\n\ts_barrier" ::: "memory");
;         const bool more = t + 1 < NS;
;         const AttnItem nxt = attn_decode<FINAL>(round_of(more ? t + 1 : t), wid);
;         attn_load(proj, nxt, kv, vv, tid);
;         attn_compute<FINAL>(lds, proj, cur, nxt, more, qf, o23, lse23, ycat, lane, wid);
;         asm volatile("s_waitcnt lgkmcnt(0)\n\ts_barrier" ::: "memory");
;         if (!more) break;
	s_cbranch_scc0 .LBB0_480
	ds_write_b128 v158, v[32:35]
	ds_write_b128 v159, v[36:39] offset:49152
	ds_write_b128 v160, v[40:43]
	ds_write_b128 v161, v[44:47] offset:49152
	ds_write_b128 v162, v[48:51]
	ds_write_b128 v163, v[52:55] offset:49152
	ds_write_b128 v164, v[56:59]
	ds_write_b128 v165, v[60:63] offset:49152
	ds_write_b128 v166, v[80:83]
	ds_write_b128 v167, v[84:87] offset:49152
	ds_write_b128 v183, v[88:91]
	ds_write_b128 v185, v[92:95] offset:49152
	s_branch .Lattn_b_ldone
